# A14: A13 + RWKV scan LDS prefetch distance 2 (three register sets)
# baseline (speedup 1.0000x reference)
.Lrw_scan_loop:
	s_and_b32 s2, s8, 1
	s_mul_i32 s3, s2, 0xe000
	s_lshl_b32 s2, s2, 12
	v_add_u32_e32 v195, s3, v103
	v_add_u32_e32 v33, s3, v38
	v_add_u32_e32 v196, s3, v75
	v_add_u32_e32 v36, s3, v37
	v_add_u32_e32 v102, s2, v76
	ds_read_b128 v[140:143], v195 offset:0
	ds_read_b128 v[152:155], v195 offset:8192
	ds_read_b128 v[176:179], v195 offset:16384
	ds_read_b128 v[84:87], v195 offset:32768
	ds_read_b64 v[4:5], v196 offset:0
	ds_read_b32 v6, v36 offset:0
	ds_read_b128 v[144:147], v195 offset:256
	ds_read_b128 v[156:159], v195 offset:8448
	ds_read_b128 v[180:183], v195 offset:16640
	ds_read_b128 v[88:91], v195 offset:33024
	ds_read_b64 v[8:9], v196 offset:512
	ds_read_b32 v10, v36 offset:512
	ds_read_b128 v[148:151], v195 offset:512
	ds_read_b128 v[160:163], v195 offset:8704
	ds_read_b128 v[184:187], v195 offset:16896
	ds_read_b128 v[92:95], v195 offset:33280
	ds_read_b64 v[12:13], v196 offset:1024
	ds_read_b32 v14, v36 offset:1024
	s_waitcnt lgkmcnt(12)
	v_pk_mul_f32 v[46:47], v[24:25], v[140:141] op_sel_hi:[0,1]
	v_pk_mul_f32 v[34:35], v[20:21], v[140:141] op_sel_hi:[0,1]
	v_pk_fma_f32 v[46:47], v[24:25], v[142:143], v[46:47] op_sel:[1,0,0] op_sel_hi:[1,1,1]
	v_pk_fma_f32 v[34:35], v[20:21], v[142:143], v[34:35] op_sel:[1,0,0] op_sel_hi:[1,1,1]
	v_pk_fma_f32 v[46:47], v[26:27], v[152:153], v[46:47] op_sel_hi:[0,1,1]
	v_pk_fma_f32 v[34:35], v[22:23], v[152:153], v[34:35] op_sel_hi:[0,1,1]
	v_pk_fma_f32 v[46:47], v[26:27], v[154:155], v[46:47] op_sel:[1,0,0] op_sel_hi:[1,1,1]
	v_pk_fma_f32 v[34:35], v[22:23], v[154:155], v[34:35] op_sel:[1,0,0] op_sel_hi:[1,1,1]
	v_pk_fma_f32 v[20:21], v[176:177], v[4:5], v[20:21] op_sel_hi:[1,0,1]
	v_add_f32_dpp v28, v46, v34 row_half_mirror row_mask:0xf bank_mask:0xf
	v_add_f32_dpp v32, v47, v35 row_half_mirror row_mask:0xf bank_mask:0xf
	v_pk_fma_f32 v[22:23], v[178:179], v[4:5], v[22:23] op_sel_hi:[1,0,1]
	v_add_f32_dpp v28, v28, v28 row_ror:8 row_mask:0xf bank_mask:0xf
	v_add_f32_dpp v32, v32, v32 row_ror:8 row_mask:0xf bank_mask:0xf
	v_pk_fma_f32 v[24:25], v[176:177], v[6:7], v[24:25] op_sel_hi:[1,0,1]
	v_add_f32_dpp v28, v28, v28 quad_perm:[1,0,3,2] row_mask:0xf bank_mask:0xf
	v_add_f32_dpp v32, v32, v32 quad_perm:[1,0,3,2] row_mask:0xf bank_mask:0xf
	v_pk_fma_f32 v[26:27], v[178:179], v[6:7], v[26:27] op_sel_hi:[1,0,1]
	v_add_f32_dpp v28, v28, v28 quad_perm:[2,3,0,1] row_mask:0xf bank_mask:0xf
	v_add_f32_dpp v32, v32, v32 quad_perm:[2,3,0,1] row_mask:0xf bank_mask:0xf
	v_add_f32_e32 v39, v32, v5
	v_mov_b32_dpp v30, v28 row_half_mirror row_mask:0xf bank_mask:0xf
	v_pk_fma_f32 v[20:21], v[84:85], v[28:29], v[20:21] op_sel_hi:[1,0,1] neg_lo:[0,1,0] neg_hi:[0,1,0]
	v_pk_fma_f32 v[22:23], v[86:87], v[28:29], v[22:23] op_sel_hi:[1,0,1] neg_lo:[0,1,0] neg_hi:[0,1,0]
	v_pk_fma_f32 v[24:25], v[84:85], v[30:31], v[24:25] op_sel_hi:[1,0,1] neg_lo:[0,1,0] neg_hi:[0,1,0]
	v_pk_fma_f32 v[26:27], v[86:87], v[30:31], v[26:27] op_sel_hi:[1,0,1] neg_lo:[0,1,0] neg_hi:[0,1,0]
	ds_write_b32 v102, v39 offset:0
	ds_read_b128 v[140:143], v195 offset:768
	ds_read_b128 v[152:155], v195 offset:8960
	ds_read_b128 v[164:167], v195 offset:25344
	ds_read_b128 v[176:179], v195 offset:17152
	ds_read_b128 v[84:87], v195 offset:33536
	ds_read_b64 v[4:5], v196 offset:1536
	ds_read_b32 v6, v36 offset:1536
	s_waitcnt lgkmcnt(14)
	v_pk_mul_f32 v[46:47], v[24:25], v[144:145] op_sel_hi:[0,1]
	v_pk_mul_f32 v[34:35], v[20:21], v[144:145] op_sel_hi:[0,1]
	v_pk_fma_f32 v[46:47], v[24:25], v[146:147], v[46:47] op_sel:[1,0,0] op_sel_hi:[1,1,1]
	v_pk_fma_f32 v[34:35], v[20:21], v[146:147], v[34:35] op_sel:[1,0,0] op_sel_hi:[1,1,1]
	v_pk_fma_f32 v[46:47], v[26:27], v[156:157], v[46:47] op_sel_hi:[0,1,1]
	v_pk_fma_f32 v[34:35], v[22:23], v[156:157], v[34:35] op_sel_hi:[0,1,1]
	v_pk_fma_f32 v[46:47], v[26:27], v[158:159], v[46:47] op_sel:[1,0,0] op_sel_hi:[1,1,1]
	v_pk_fma_f32 v[34:35], v[22:23], v[158:159], v[34:35] op_sel:[1,0,0] op_sel_hi:[1,1,1]
	v_pk_fma_f32 v[20:21], v[180:181], v[8:9], v[20:21] op_sel_hi:[1,0,1]
	v_add_f32_dpp v28, v46, v34 row_half_mirror row_mask:0xf bank_mask:0xf
	v_add_f32_dpp v32, v47, v35 row_half_mirror row_mask:0xf bank_mask:0xf
	v_pk_fma_f32 v[22:23], v[182:183], v[8:9], v[22:23] op_sel_hi:[1,0,1]
	v_add_f32_dpp v28, v28, v28 row_ror:8 row_mask:0xf bank_mask:0xf
	v_add_f32_dpp v32, v32, v32 row_ror:8 row_mask:0xf bank_mask:0xf
	v_pk_fma_f32 v[24:25], v[180:181], v[10:11], v[24:25] op_sel_hi:[1,0,1]
	v_add_f32_dpp v28, v28, v28 quad_perm:[1,0,3,2] row_mask:0xf bank_mask:0xf
	v_add_f32_dpp v32, v32, v32 quad_perm:[1,0,3,2] row_mask:0xf bank_mask:0xf
	v_pk_fma_f32 v[26:27], v[182:183], v[10:11], v[26:27] op_sel_hi:[1,0,1]
	v_add_f32_dpp v28, v28, v28 quad_perm:[2,3,0,1] row_mask:0xf bank_mask:0xf
	v_add_f32_dpp v32, v32, v32 quad_perm:[2,3,0,1] row_mask:0xf bank_mask:0xf
	v_add_f32_e32 v39, v32, v9
	v_mov_b32_dpp v30, v28 row_half_mirror row_mask:0xf bank_mask:0xf
	v_pk_fma_f32 v[20:21], v[88:89], v[28:29], v[20:21] op_sel_hi:[1,0,1] neg_lo:[0,1,0] neg_hi:[0,1,0]
	v_pk_fma_f32 v[22:23], v[90:91], v[28:29], v[22:23] op_sel_hi:[1,0,1] neg_lo:[0,1,0] neg_hi:[0,1,0]
	v_pk_fma_f32 v[24:25], v[88:89], v[30:31], v[24:25] op_sel_hi:[1,0,1] neg_lo:[0,1,0] neg_hi:[0,1,0]
	v_pk_fma_f32 v[26:27], v[90:91], v[30:31], v[26:27] op_sel_hi:[1,0,1] neg_lo:[0,1,0] neg_hi:[0,1,0]
	ds_write_b32 v102, v39 offset:128
	ds_read_b128 v[144:147], v195 offset:1024
	ds_read_b128 v[156:159], v195 offset:9216
	ds_read_b128 v[180:183], v195 offset:17408
	ds_read_b128 v[88:91], v195 offset:33792
	ds_read_b64 v[8:9], v196 offset:2048
	ds_read_b32 v10, v36 offset:2048
	s_waitcnt lgkmcnt(15)
	v_pk_mul_f32 v[46:47], v[24:25], v[148:149] op_sel_hi:[0,1]
	v_pk_mul_f32 v[34:35], v[20:21], v[148:149] op_sel_hi:[0,1]
	v_pk_fma_f32 v[46:47], v[24:25], v[150:151], v[46:47] op_sel:[1,0,0] op_sel_hi:[1,1,1]
	v_pk_fma_f32 v[34:35], v[20:21], v[150:151], v[34:35] op_sel:[1,0,0] op_sel_hi:[1,1,1]
	v_pk_fma_f32 v[46:47], v[26:27], v[160:161], v[46:47] op_sel_hi:[0,1,1]
	v_pk_fma_f32 v[34:35], v[22:23], v[160:161], v[34:35] op_sel_hi:[0,1,1]
	v_pk_fma_f32 v[46:47], v[26:27], v[162:163], v[46:47] op_sel:[1,0,0] op_sel_hi:[1,1,1]
	v_pk_fma_f32 v[34:35], v[22:23], v[162:163], v[34:35] op_sel:[1,0,0] op_sel_hi:[1,1,1]
	v_pk_fma_f32 v[20:21], v[184:185], v[12:13], v[20:21] op_sel_hi:[1,0,1]
	v_add_f32_dpp v28, v46, v34 row_half_mirror row_mask:0xf bank_mask:0xf
	v_add_f32_dpp v32, v47, v35 row_half_mirror row_mask:0xf bank_mask:0xf
	v_pk_fma_f32 v[22:23], v[186:187], v[12:13], v[22:23] op_sel_hi:[1,0,1]
	v_add_f32_dpp v28, v28, v28 row_ror:8 row_mask:0xf bank_mask:0xf
	v_add_f32_dpp v32, v32, v32 row_ror:8 row_mask:0xf bank_mask:0xf
	v_pk_fma_f32 v[24:25], v[184:185], v[14:15], v[24:25] op_sel_hi:[1,0,1]
	v_add_f32_dpp v28, v28, v28 quad_perm:[1,0,3,2] row_mask:0xf bank_mask:0xf
	v_add_f32_dpp v32, v32, v32 quad_perm:[1,0,3,2] row_mask:0xf bank_mask:0xf
	v_pk_fma_f32 v[26:27], v[186:187], v[14:15], v[26:27] op_sel_hi:[1,0,1]
	v_add_f32_dpp v28, v28, v28 quad_perm:[2,3,0,1] row_mask:0xf bank_mask:0xf
	v_add_f32_dpp v32, v32, v32 quad_perm:[2,3,0,1] row_mask:0xf bank_mask:0xf
	v_add_f32_e32 v39, v32, v13
	v_mov_b32_dpp v30, v28 row_half_mirror row_mask:0xf bank_mask:0xf
	v_pk_fma_f32 v[20:21], v[92:93], v[28:29], v[20:21] op_sel_hi:[1,0,1] neg_lo:[0,1,0] neg_hi:[0,1,0]
	v_pk_fma_f32 v[22:23], v[94:95], v[28:29], v[22:23] op_sel_hi:[1,0,1] neg_lo:[0,1,0] neg_hi:[0,1,0]
	v_pk_fma_f32 v[24:25], v[92:93], v[30:31], v[24:25] op_sel_hi:[1,0,1] neg_lo:[0,1,0] neg_hi:[0,1,0]
	v_pk_fma_f32 v[26:27], v[94:95], v[30:31], v[26:27] op_sel_hi:[1,0,1] neg_lo:[0,1,0] neg_hi:[0,1,0]
	ds_write_b32 v102, v39 offset:256
	ds_read_b128 v[148:151], v195 offset:1280
	ds_read_b128 v[160:163], v195 offset:9472
	ds_read_b128 v[184:187], v195 offset:17664
	ds_read_b128 v[92:95], v195 offset:34048
	ds_read_b64 v[12:13], v196 offset:2560
	ds_read_b32 v14, v36 offset:2560
	s_waitcnt lgkmcnt(14)
	v_pk_mul_f32 v[46:47], v[24:25], v[140:141] op_sel_hi:[0,1]
	v_pk_mul_f32 v[34:35], v[20:21], v[140:141] op_sel_hi:[0,1]
	v_pk_fma_f32 v[46:47], v[24:25], v[142:143], v[46:47] op_sel:[1,0,0] op_sel_hi:[1,1,1]
	v_pk_fma_f32 v[34:35], v[20:21], v[142:143], v[34:35] op_sel:[1,0,0] op_sel_hi:[1,1,1]
	v_pk_fma_f32 v[46:47], v[26:27], v[152:153], v[46:47] op_sel_hi:[0,1,1]
	v_pk_fma_f32 v[34:35], v[22:23], v[152:153], v[34:35] op_sel_hi:[0,1,1]
	v_pk_fma_f32 v[46:47], v[26:27], v[154:155], v[46:47] op_sel:[1,0,0] op_sel_hi:[1,1,1]
	v_pk_fma_f32 v[34:35], v[22:23], v[154:155], v[34:35] op_sel:[1,0,0] op_sel_hi:[1,1,1]
	v_pk_mul_f32 v[20:21], v[20:21], v[164:165]
	v_add_f32_dpp v28, v46, v34 row_half_mirror row_mask:0xf bank_mask:0xf
	v_add_f32_dpp v32, v47, v35 row_half_mirror row_mask:0xf bank_mask:0xf
	v_pk_mul_f32 v[22:23], v[22:23], v[166:167]
	v_add_f32_dpp v28, v28, v28 row_ror:8 row_mask:0xf bank_mask:0xf
	v_add_f32_dpp v32, v32, v32 row_ror:8 row_mask:0xf bank_mask:0xf
	v_pk_mul_f32 v[24:25], v[24:25], v[164:165]
	v_add_f32_dpp v28, v28, v28 quad_perm:[1,0,3,2] row_mask:0xf bank_mask:0xf
	v_add_f32_dpp v32, v32, v32 quad_perm:[1,0,3,2] row_mask:0xf bank_mask:0xf
	v_pk_mul_f32 v[26:27], v[26:27], v[166:167]
	v_add_f32_dpp v28, v28, v28 quad_perm:[2,3,0,1] row_mask:0xf bank_mask:0xf
	v_add_f32_dpp v32, v32, v32 quad_perm:[2,3,0,1] row_mask:0xf bank_mask:0xf
	v_pk_fma_f32 v[20:21], v[176:177], v[4:5], v[20:21] op_sel_hi:[1,0,1]
	v_mov_b32_dpp v30, v28 row_half_mirror row_mask:0xf bank_mask:0xf
	v_pk_fma_f32 v[22:23], v[178:179], v[4:5], v[22:23] op_sel_hi:[1,0,1]
	v_pk_fma_f32 v[24:25], v[176:177], v[6:7], v[24:25] op_sel_hi:[1,0,1]
	v_pk_fma_f32 v[26:27], v[178:179], v[6:7], v[26:27] op_sel_hi:[1,0,1]
	v_pk_fma_f32 v[20:21], v[84:85], v[28:29], v[20:21] op_sel_hi:[1,0,1] neg_lo:[0,1,0] neg_hi:[0,1,0]
	v_pk_fma_f32 v[22:23], v[86:87], v[28:29], v[22:23] op_sel_hi:[1,0,1] neg_lo:[0,1,0] neg_hi:[0,1,0]
	v_pk_fma_f32 v[24:25], v[84:85], v[30:31], v[24:25] op_sel_hi:[1,0,1] neg_lo:[0,1,0] neg_hi:[0,1,0]
	v_pk_fma_f32 v[26:27], v[86:87], v[30:31], v[26:27] op_sel_hi:[1,0,1] neg_lo:[0,1,0] neg_hi:[0,1,0]
	v_add_f32_e32 v39, v32, v5
	ds_write_b32 v102, v39 offset:384
	ds_read_b128 v[140:143], v195 offset:1536
	ds_read_b128 v[152:155], v195 offset:9728
	ds_read_b128 v[176:179], v195 offset:17920
	ds_read_b128 v[84:87], v195 offset:34304
	ds_read_b64 v[4:5], v196 offset:3072
	ds_read_b32 v6, v36 offset:3072
	s_waitcnt lgkmcnt(14)
	v_pk_mul_f32 v[46:47], v[24:25], v[144:145] op_sel_hi:[0,1]
	v_pk_mul_f32 v[34:35], v[20:21], v[144:145] op_sel_hi:[0,1]
	v_pk_fma_f32 v[46:47], v[24:25], v[146:147], v[46:47] op_sel:[1,0,0] op_sel_hi:[1,1,1]
	v_pk_fma_f32 v[34:35], v[20:21], v[146:147], v[34:35] op_sel:[1,0,0] op_sel_hi:[1,1,1]
	v_pk_fma_f32 v[46:47], v[26:27], v[156:157], v[46:47] op_sel_hi:[0,1,1]
	v_pk_fma_f32 v[34:35], v[22:23], v[156:157], v[34:35] op_sel_hi:[0,1,1]
	v_pk_fma_f32 v[46:47], v[26:27], v[158:159], v[46:47] op_sel:[1,0,0] op_sel_hi:[1,1,1]
	v_pk_fma_f32 v[34:35], v[22:23], v[158:159], v[34:35] op_sel:[1,0,0] op_sel_hi:[1,1,1]
	v_pk_fma_f32 v[20:21], v[180:181], v[8:9], v[20:21] op_sel_hi:[1,0,1]
	v_add_f32_dpp v28, v46, v34 row_half_mirror row_mask:0xf bank_mask:0xf
	v_add_f32_dpp v32, v47, v35 row_half_mirror row_mask:0xf bank_mask:0xf
	v_pk_fma_f32 v[22:23], v[182:183], v[8:9], v[22:23] op_sel_hi:[1,0,1]
	v_add_f32_dpp v28, v28, v28 row_ror:8 row_mask:0xf bank_mask:0xf
	v_add_f32_dpp v32, v32, v32 row_ror:8 row_mask:0xf bank_mask:0xf
	v_pk_fma_f32 v[24:25], v[180:181], v[10:11], v[24:25] op_sel_hi:[1,0,1]
	v_add_f32_dpp v28, v28, v28 quad_perm:[1,0,3,2] row_mask:0xf bank_mask:0xf
	v_add_f32_dpp v32, v32, v32 quad_perm:[1,0,3,2] row_mask:0xf bank_mask:0xf
	v_pk_fma_f32 v[26:27], v[182:183], v[10:11], v[26:27] op_sel_hi:[1,0,1]
	v_add_f32_dpp v28, v28, v28 quad_perm:[2,3,0,1] row_mask:0xf bank_mask:0xf
	v_add_f32_dpp v32, v32, v32 quad_perm:[2,3,0,1] row_mask:0xf bank_mask:0xf
	v_add_f32_e32 v39, v32, v9
	v_mov_b32_dpp v30, v28 row_half_mirror row_mask:0xf bank_mask:0xf
	v_pk_fma_f32 v[20:21], v[88:89], v[28:29], v[20:21] op_sel_hi:[1,0,1] neg_lo:[0,1,0] neg_hi:[0,1,0]
	v_pk_fma_f32 v[22:23], v[90:91], v[28:29], v[22:23] op_sel_hi:[1,0,1] neg_lo:[0,1,0] neg_hi:[0,1,0]
	v_pk_fma_f32 v[24:25], v[88:89], v[30:31], v[24:25] op_sel_hi:[1,0,1] neg_lo:[0,1,0] neg_hi:[0,1,0]
	v_pk_fma_f32 v[26:27], v[90:91], v[30:31], v[26:27] op_sel_hi:[1,0,1] neg_lo:[0,1,0] neg_hi:[0,1,0]
	ds_write_b32 v102, v39 offset:512
	ds_read_b128 v[144:147], v195 offset:1792
	ds_read_b128 v[156:159], v195 offset:9984
	ds_read_b128 v[168:171], v195 offset:26368
	ds_read_b128 v[180:183], v195 offset:18176
	ds_read_b128 v[88:91], v195 offset:34560
	ds_read_b64 v[8:9], v196 offset:3584
	ds_read_b32 v10, v36 offset:3584
	s_waitcnt lgkmcnt(15)
	v_pk_mul_f32 v[46:47], v[24:25], v[148:149] op_sel_hi:[0,1]
	v_pk_mul_f32 v[34:35], v[20:21], v[148:149] op_sel_hi:[0,1]
	v_pk_fma_f32 v[46:47], v[24:25], v[150:151], v[46:47] op_sel:[1,0,0] op_sel_hi:[1,1,1]
	v_pk_fma_f32 v[34:35], v[20:21], v[150:151], v[34:35] op_sel:[1,0,0] op_sel_hi:[1,1,1]
	v_pk_fma_f32 v[46:47], v[26:27], v[160:161], v[46:47] op_sel_hi:[0,1,1]
	v_pk_fma_f32 v[34:35], v[22:23], v[160:161], v[34:35] op_sel_hi:[0,1,1]
	v_pk_fma_f32 v[46:47], v[26:27], v[162:163], v[46:47] op_sel:[1,0,0] op_sel_hi:[1,1,1]
	v_pk_fma_f32 v[34:35], v[22:23], v[162:163], v[34:35] op_sel:[1,0,0] op_sel_hi:[1,1,1]
	v_pk_fma_f32 v[20:21], v[184:185], v[12:13], v[20:21] op_sel_hi:[1,0,1]
	v_add_f32_dpp v28, v46, v34 row_half_mirror row_mask:0xf bank_mask:0xf
	v_add_f32_dpp v32, v47, v35 row_half_mirror row_mask:0xf bank_mask:0xf
	v_pk_fma_f32 v[22:23], v[186:187], v[12:13], v[22:23] op_sel_hi:[1,0,1]
	v_add_f32_dpp v28, v28, v28 row_ror:8 row_mask:0xf bank_mask:0xf
	v_add_f32_dpp v32, v32, v32 row_ror:8 row_mask:0xf bank_mask:0xf
	v_pk_fma_f32 v[24:25], v[184:185], v[14:15], v[24:25] op_sel_hi:[1,0,1]
	v_add_f32_dpp v28, v28, v28 quad_perm:[1,0,3,2] row_mask:0xf bank_mask:0xf
	v_add_f32_dpp v32, v32, v32 quad_perm:[1,0,3,2] row_mask:0xf bank_mask:0xf
	v_pk_fma_f32 v[26:27], v[186:187], v[14:15], v[26:27] op_sel_hi:[1,0,1]
	v_add_f32_dpp v28, v28, v28 quad_perm:[2,3,0,1] row_mask:0xf bank_mask:0xf
	v_add_f32_dpp v32, v32, v32 quad_perm:[2,3,0,1] row_mask:0xf bank_mask:0xf
	v_add_f32_e32 v39, v32, v13
	v_mov_b32_dpp v30, v28 row_half_mirror row_mask:0xf bank_mask:0xf
	v_pk_fma_f32 v[20:21], v[92:93], v[28:29], v[20:21] op_sel_hi:[1,0,1] neg_lo:[0,1,0] neg_hi:[0,1,0]
	v_pk_fma_f32 v[22:23], v[94:95], v[28:29], v[22:23] op_sel_hi:[1,0,1] neg_lo:[0,1,0] neg_hi:[0,1,0]
	v_pk_fma_f32 v[24:25], v[92:93], v[30:31], v[24:25] op_sel_hi:[1,0,1] neg_lo:[0,1,0] neg_hi:[0,1,0]
	v_pk_fma_f32 v[26:27], v[94:95], v[30:31], v[26:27] op_sel_hi:[1,0,1] neg_lo:[0,1,0] neg_hi:[0,1,0]
	ds_write_b32 v102, v39 offset:640
	ds_read_b128 v[148:151], v195 offset:2048
	ds_read_b128 v[160:163], v195 offset:10240
	ds_read_b128 v[184:187], v195 offset:18432
	ds_read_b128 v[92:95], v195 offset:34816
	ds_read_b64 v[12:13], v196 offset:4096
	ds_read_b32 v14, v36 offset:4096
	s_waitcnt lgkmcnt(15)
	v_pk_mul_f32 v[46:47], v[24:25], v[140:141] op_sel_hi:[0,1]
	v_pk_mul_f32 v[34:35], v[20:21], v[140:141] op_sel_hi:[0,1]
	v_pk_fma_f32 v[46:47], v[24:25], v[142:143], v[46:47] op_sel:[1,0,0] op_sel_hi:[1,1,1]
	v_pk_fma_f32 v[34:35], v[20:21], v[142:143], v[34:35] op_sel:[1,0,0] op_sel_hi:[1,1,1]
	v_pk_fma_f32 v[46:47], v[26:27], v[152:153], v[46:47] op_sel_hi:[0,1,1]
	v_pk_fma_f32 v[34:35], v[22:23], v[152:153], v[34:35] op_sel_hi:[0,1,1]
	v_pk_fma_f32 v[46:47], v[26:27], v[154:155], v[46:47] op_sel:[1,0,0] op_sel_hi:[1,1,1]
	v_pk_fma_f32 v[34:35], v[22:23], v[154:155], v[34:35] op_sel:[1,0,0] op_sel_hi:[1,1,1]
	v_pk_fma_f32 v[20:21], v[176:177], v[4:5], v[20:21] op_sel_hi:[1,0,1]
	v_add_f32_dpp v28, v46, v34 row_half_mirror row_mask:0xf bank_mask:0xf
	v_add_f32_dpp v32, v47, v35 row_half_mirror row_mask:0xf bank_mask:0xf
	v_pk_fma_f32 v[22:23], v[178:179], v[4:5], v[22:23] op_sel_hi:[1,0,1]
	v_add_f32_dpp v28, v28, v28 row_ror:8 row_mask:0xf bank_mask:0xf
	v_add_f32_dpp v32, v32, v32 row_ror:8 row_mask:0xf bank_mask:0xf
	v_pk_fma_f32 v[24:25], v[176:177], v[6:7], v[24:25] op_sel_hi:[1,0,1]
	v_add_f32_dpp v28, v28, v28 quad_perm:[1,0,3,2] row_mask:0xf bank_mask:0xf
	v_add_f32_dpp v32, v32, v32 quad_perm:[1,0,3,2] row_mask:0xf bank_mask:0xf
	v_pk_fma_f32 v[26:27], v[178:179], v[6:7], v[26:27] op_sel_hi:[1,0,1]
	v_add_f32_dpp v28, v28, v28 quad_perm:[2,3,0,1] row_mask:0xf bank_mask:0xf
	v_add_f32_dpp v32, v32, v32 quad_perm:[2,3,0,1] row_mask:0xf bank_mask:0xf
	v_add_f32_e32 v39, v32, v5
	v_mov_b32_dpp v30, v28 row_half_mirror row_mask:0xf bank_mask:0xf
	v_pk_fma_f32 v[20:21], v[84:85], v[28:29], v[20:21] op_sel_hi:[1,0,1] neg_lo:[0,1,0] neg_hi:[0,1,0]
	v_pk_fma_f32 v[22:23], v[86:87], v[28:29], v[22:23] op_sel_hi:[1,0,1] neg_lo:[0,1,0] neg_hi:[0,1,0]
	v_pk_fma_f32 v[24:25], v[84:85], v[30:31], v[24:25] op_sel_hi:[1,0,1] neg_lo:[0,1,0] neg_hi:[0,1,0]
	v_pk_fma_f32 v[26:27], v[86:87], v[30:31], v[26:27] op_sel_hi:[1,0,1] neg_lo:[0,1,0] neg_hi:[0,1,0]
	ds_write_b32 v102, v39 offset:768
	ds_read_b128 v[140:143], v195 offset:2304
	ds_read_b128 v[152:155], v195 offset:10496
	ds_read_b128 v[176:179], v195 offset:18688
	ds_read_b128 v[84:87], v195 offset:35072
	ds_read_b64 v[4:5], v196 offset:4608
	ds_read_b32 v6, v36 offset:4608
	s_waitcnt lgkmcnt(14)
	v_pk_mul_f32 v[46:47], v[24:25], v[144:145] op_sel_hi:[0,1]
	v_pk_mul_f32 v[34:35], v[20:21], v[144:145] op_sel_hi:[0,1]
	v_pk_fma_f32 v[46:47], v[24:25], v[146:147], v[46:47] op_sel:[1,0,0] op_sel_hi:[1,1,1]
	v_pk_fma_f32 v[34:35], v[20:21], v[146:147], v[34:35] op_sel:[1,0,0] op_sel_hi:[1,1,1]
	v_pk_fma_f32 v[46:47], v[26:27], v[156:157], v[46:47] op_sel_hi:[0,1,1]
	v_pk_fma_f32 v[34:35], v[22:23], v[156:157], v[34:35] op_sel_hi:[0,1,1]
	v_pk_fma_f32 v[46:47], v[26:27], v[158:159], v[46:47] op_sel:[1,0,0] op_sel_hi:[1,1,1]
	v_pk_fma_f32 v[34:35], v[22:23], v[158:159], v[34:35] op_sel:[1,0,0] op_sel_hi:[1,1,1]
	v_pk_mul_f32 v[20:21], v[20:21], v[168:169]
	v_add_f32_dpp v28, v46, v34 row_half_mirror row_mask:0xf bank_mask:0xf
	v_add_f32_dpp v32, v47, v35 row_half_mirror row_mask:0xf bank_mask:0xf
	v_pk_mul_f32 v[22:23], v[22:23], v[170:171]
	v_add_f32_dpp v28, v28, v28 row_ror:8 row_mask:0xf bank_mask:0xf
	v_add_f32_dpp v32, v32, v32 row_ror:8 row_mask:0xf bank_mask:0xf
	v_pk_mul_f32 v[24:25], v[24:25], v[168:169]
	v_add_f32_dpp v28, v28, v28 quad_perm:[1,0,3,2] row_mask:0xf bank_mask:0xf
	v_add_f32_dpp v32, v32, v32 quad_perm:[1,0,3,2] row_mask:0xf bank_mask:0xf
	v_pk_mul_f32 v[26:27], v[26:27], v[170:171]
	v_add_f32_dpp v28, v28, v28 quad_perm:[2,3,0,1] row_mask:0xf bank_mask:0xf
	v_add_f32_dpp v32, v32, v32 quad_perm:[2,3,0,1] row_mask:0xf bank_mask:0xf
	v_pk_fma_f32 v[20:21], v[180:181], v[8:9], v[20:21] op_sel_hi:[1,0,1]
	v_mov_b32_dpp v30, v28 row_half_mirror row_mask:0xf bank_mask:0xf
	v_pk_fma_f32 v[22:23], v[182:183], v[8:9], v[22:23] op_sel_hi:[1,0,1]
	v_pk_fma_f32 v[24:25], v[180:181], v[10:11], v[24:25] op_sel_hi:[1,0,1]
	v_pk_fma_f32 v[26:27], v[182:183], v[10:11], v[26:27] op_sel_hi:[1,0,1]
	v_pk_fma_f32 v[20:21], v[88:89], v[28:29], v[20:21] op_sel_hi:[1,0,1] neg_lo:[0,1,0] neg_hi:[0,1,0]
	v_pk_fma_f32 v[22:23], v[90:91], v[28:29], v[22:23] op_sel_hi:[1,0,1] neg_lo:[0,1,0] neg_hi:[0,1,0]
	v_pk_fma_f32 v[24:25], v[88:89], v[30:31], v[24:25] op_sel_hi:[1,0,1] neg_lo:[0,1,0] neg_hi:[0,1,0]
	v_pk_fma_f32 v[26:27], v[90:91], v[30:31], v[26:27] op_sel_hi:[1,0,1] neg_lo:[0,1,0] neg_hi:[0,1,0]
	v_add_f32_e32 v39, v32, v9
	ds_write_b32 v102, v39 offset:896
	ds_read_b128 v[144:147], v195 offset:2560
	ds_read_b128 v[156:159], v195 offset:10752
	ds_read_b128 v[180:183], v195 offset:18944
	ds_read_b128 v[88:91], v195 offset:35328
	ds_read_b64 v[8:9], v196 offset:5120
	ds_read_b32 v10, v36 offset:5120
	s_waitcnt lgkmcnt(14)
	v_pk_mul_f32 v[46:47], v[24:25], v[148:149] op_sel_hi:[0,1]
	v_pk_mul_f32 v[34:35], v[20:21], v[148:149] op_sel_hi:[0,1]
	v_pk_fma_f32 v[46:47], v[24:25], v[150:151], v[46:47] op_sel:[1,0,0] op_sel_hi:[1,1,1]
	v_pk_fma_f32 v[34:35], v[20:21], v[150:151], v[34:35] op_sel:[1,0,0] op_sel_hi:[1,1,1]
	v_pk_fma_f32 v[46:47], v[26:27], v[160:161], v[46:47] op_sel_hi:[0,1,1]
	v_pk_fma_f32 v[34:35], v[22:23], v[160:161], v[34:35] op_sel_hi:[0,1,1]
	v_pk_fma_f32 v[46:47], v[26:27], v[162:163], v[46:47] op_sel:[1,0,0] op_sel_hi:[1,1,1]
	v_pk_fma_f32 v[34:35], v[22:23], v[162:163], v[34:35] op_sel:[1,0,0] op_sel_hi:[1,1,1]
	v_pk_fma_f32 v[20:21], v[184:185], v[12:13], v[20:21] op_sel_hi:[1,0,1]
	v_add_f32_dpp v28, v46, v34 row_half_mirror row_mask:0xf bank_mask:0xf
	v_add_f32_dpp v32, v47, v35 row_half_mirror row_mask:0xf bank_mask:0xf
	v_pk_fma_f32 v[22:23], v[186:187], v[12:13], v[22:23] op_sel_hi:[1,0,1]
	v_add_f32_dpp v28, v28, v28 row_ror:8 row_mask:0xf bank_mask:0xf
	v_add_f32_dpp v32, v32, v32 row_ror:8 row_mask:0xf bank_mask:0xf
	v_pk_fma_f32 v[24:25], v[184:185], v[14:15], v[24:25] op_sel_hi:[1,0,1]
	v_add_f32_dpp v28, v28, v28 quad_perm:[1,0,3,2] row_mask:0xf bank_mask:0xf
	v_add_f32_dpp v32, v32, v32 quad_perm:[1,0,3,2] row_mask:0xf bank_mask:0xf
	v_pk_fma_f32 v[26:27], v[186:187], v[14:15], v[26:27] op_sel_hi:[1,0,1]
	v_add_f32_dpp v28, v28, v28 quad_perm:[2,3,0,1] row_mask:0xf bank_mask:0xf
	v_add_f32_dpp v32, v32, v32 quad_perm:[2,3,0,1] row_mask:0xf bank_mask:0xf
	v_add_f32_e32 v39, v32, v13
	v_mov_b32_dpp v30, v28 row_half_mirror row_mask:0xf bank_mask:0xf
	v_pk_fma_f32 v[20:21], v[92:93], v[28:29], v[20:21] op_sel_hi:[1,0,1] neg_lo:[0,1,0] neg_hi:[0,1,0]
	v_pk_fma_f32 v[22:23], v[94:95], v[28:29], v[22:23] op_sel_hi:[1,0,1] neg_lo:[0,1,0] neg_hi:[0,1,0]
	v_pk_fma_f32 v[24:25], v[92:93], v[30:31], v[24:25] op_sel_hi:[1,0,1] neg_lo:[0,1,0] neg_hi:[0,1,0]
	v_pk_fma_f32 v[26:27], v[94:95], v[30:31], v[26:27] op_sel_hi:[1,0,1] neg_lo:[0,1,0] neg_hi:[0,1,0]
	ds_write_b32 v102, v39 offset:1024
	ds_read_b128 v[148:151], v195 offset:2816
	ds_read_b128 v[160:163], v195 offset:11008
	ds_read_b128 v[172:175], v195 offset:27392
	ds_read_b128 v[184:187], v195 offset:19200
	ds_read_b128 v[92:95], v195 offset:35584
	ds_read_b64 v[12:13], v196 offset:5632
	ds_read_b32 v14, v36 offset:5632
	s_waitcnt lgkmcnt(15)
	v_pk_mul_f32 v[46:47], v[24:25], v[140:141] op_sel_hi:[0,1]
	v_pk_mul_f32 v[34:35], v[20:21], v[140:141] op_sel_hi:[0,1]
	v_pk_fma_f32 v[46:47], v[24:25], v[142:143], v[46:47] op_sel:[1,0,0] op_sel_hi:[1,1,1]
	v_pk_fma_f32 v[34:35], v[20:21], v[142:143], v[34:35] op_sel:[1,0,0] op_sel_hi:[1,1,1]
	v_pk_fma_f32 v[46:47], v[26:27], v[152:153], v[46:47] op_sel_hi:[0,1,1]
	v_pk_fma_f32 v[34:35], v[22:23], v[152:153], v[34:35] op_sel_hi:[0,1,1]
	v_pk_fma_f32 v[46:47], v[26:27], v[154:155], v[46:47] op_sel:[1,0,0] op_sel_hi:[1,1,1]
	v_pk_fma_f32 v[34:35], v[22:23], v[154:155], v[34:35] op_sel:[1,0,0] op_sel_hi:[1,1,1]
	v_pk_fma_f32 v[20:21], v[176:177], v[4:5], v[20:21] op_sel_hi:[1,0,1]
	v_add_f32_dpp v28, v46, v34 row_half_mirror row_mask:0xf bank_mask:0xf
	v_add_f32_dpp v32, v47, v35 row_half_mirror row_mask:0xf bank_mask:0xf
	v_pk_fma_f32 v[22:23], v[178:179], v[4:5], v[22:23] op_sel_hi:[1,0,1]
	v_add_f32_dpp v28, v28, v28 row_ror:8 row_mask:0xf bank_mask:0xf
	v_add_f32_dpp v32, v32, v32 row_ror:8 row_mask:0xf bank_mask:0xf
	v_pk_fma_f32 v[24:25], v[176:177], v[6:7], v[24:25] op_sel_hi:[1,0,1]
	v_add_f32_dpp v28, v28, v28 quad_perm:[1,0,3,2] row_mask:0xf bank_mask:0xf
	v_add_f32_dpp v32, v32, v32 quad_perm:[1,0,3,2] row_mask:0xf bank_mask:0xf
	v_pk_fma_f32 v[26:27], v[178:179], v[6:7], v[26:27] op_sel_hi:[1,0,1]
	v_add_f32_dpp v28, v28, v28 quad_perm:[2,3,0,1] row_mask:0xf bank_mask:0xf
	v_add_f32_dpp v32, v32, v32 quad_perm:[2,3,0,1] row_mask:0xf bank_mask:0xf
	v_add_f32_e32 v39, v32, v5
	v_mov_b32_dpp v30, v28 row_half_mirror row_mask:0xf bank_mask:0xf
	v_pk_fma_f32 v[20:21], v[84:85], v[28:29], v[20:21] op_sel_hi:[1,0,1] neg_lo:[0,1,0] neg_hi:[0,1,0]
	v_pk_fma_f32 v[22:23], v[86:87], v[28:29], v[22:23] op_sel_hi:[1,0,1] neg_lo:[0,1,0] neg_hi:[0,1,0]
	v_pk_fma_f32 v[24:25], v[84:85], v[30:31], v[24:25] op_sel_hi:[1,0,1] neg_lo:[0,1,0] neg_hi:[0,1,0]
	v_pk_fma_f32 v[26:27], v[86:87], v[30:31], v[26:27] op_sel_hi:[1,0,1] neg_lo:[0,1,0] neg_hi:[0,1,0]
	ds_write_b32 v102, v39 offset:1152
	ds_read_b128 v[140:143], v195 offset:3072
	ds_read_b128 v[152:155], v195 offset:11264
	ds_read_b128 v[176:179], v195 offset:19456
	ds_read_b128 v[84:87], v195 offset:35840
	ds_read_b64 v[4:5], v196 offset:6144
	ds_read_b32 v6, v36 offset:6144
	s_waitcnt lgkmcnt(15)
	v_pk_mul_f32 v[46:47], v[24:25], v[144:145] op_sel_hi:[0,1]
	v_pk_mul_f32 v[34:35], v[20:21], v[144:145] op_sel_hi:[0,1]
	v_pk_fma_f32 v[46:47], v[24:25], v[146:147], v[46:47] op_sel:[1,0,0] op_sel_hi:[1,1,1]
	v_pk_fma_f32 v[34:35], v[20:21], v[146:147], v[34:35] op_sel:[1,0,0] op_sel_hi:[1,1,1]
	v_pk_fma_f32 v[46:47], v[26:27], v[156:157], v[46:47] op_sel_hi:[0,1,1]
	v_pk_fma_f32 v[34:35], v[22:23], v[156:157], v[34:35] op_sel_hi:[0,1,1]
	v_pk_fma_f32 v[46:47], v[26:27], v[158:159], v[46:47] op_sel:[1,0,0] op_sel_hi:[1,1,1]
	v_pk_fma_f32 v[34:35], v[22:23], v[158:159], v[34:35] op_sel:[1,0,0] op_sel_hi:[1,1,1]
	v_pk_fma_f32 v[20:21], v[180:181], v[8:9], v[20:21] op_sel_hi:[1,0,1]
	v_add_f32_dpp v28, v46, v34 row_half_mirror row_mask:0xf bank_mask:0xf
	v_add_f32_dpp v32, v47, v35 row_half_mirror row_mask:0xf bank_mask:0xf
	v_pk_fma_f32 v[22:23], v[182:183], v[8:9], v[22:23] op_sel_hi:[1,0,1]
	v_add_f32_dpp v28, v28, v28 row_ror:8 row_mask:0xf bank_mask:0xf
	v_add_f32_dpp v32, v32, v32 row_ror:8 row_mask:0xf bank_mask:0xf
	v_pk_fma_f32 v[24:25], v[180:181], v[10:11], v[24:25] op_sel_hi:[1,0,1]
	v_add_f32_dpp v28, v28, v28 quad_perm:[1,0,3,2] row_mask:0xf bank_mask:0xf
	v_add_f32_dpp v32, v32, v32 quad_perm:[1,0,3,2] row_mask:0xf bank_mask:0xf
	v_pk_fma_f32 v[26:27], v[182:183], v[10:11], v[26:27] op_sel_hi:[1,0,1]
	v_add_f32_dpp v28, v28, v28 quad_perm:[2,3,0,1] row_mask:0xf bank_mask:0xf
	v_add_f32_dpp v32, v32, v32 quad_perm:[2,3,0,1] row_mask:0xf bank_mask:0xf
	v_add_f32_e32 v39, v32, v9
	v_mov_b32_dpp v30, v28 row_half_mirror row_mask:0xf bank_mask:0xf
	v_pk_fma_f32 v[20:21], v[88:89], v[28:29], v[20:21] op_sel_hi:[1,0,1] neg_lo:[0,1,0] neg_hi:[0,1,0]
	v_pk_fma_f32 v[22:23], v[90:91], v[28:29], v[22:23] op_sel_hi:[1,0,1] neg_lo:[0,1,0] neg_hi:[0,1,0]
	v_pk_fma_f32 v[24:25], v[88:89], v[30:31], v[24:25] op_sel_hi:[1,0,1] neg_lo:[0,1,0] neg_hi:[0,1,0]
	v_pk_fma_f32 v[26:27], v[90:91], v[30:31], v[26:27] op_sel_hi:[1,0,1] neg_lo:[0,1,0] neg_hi:[0,1,0]
	ds_write_b32 v102, v39 offset:1280
	ds_read_b128 v[144:147], v195 offset:3328
	ds_read_b128 v[156:159], v195 offset:11520
	ds_read_b128 v[180:183], v195 offset:19712
	ds_read_b128 v[88:91], v195 offset:36096
	ds_read_b64 v[8:9], v196 offset:6656
	ds_read_b32 v10, v36 offset:6656
	s_waitcnt lgkmcnt(14)
	v_pk_mul_f32 v[46:47], v[24:25], v[148:149] op_sel_hi:[0,1]
	v_pk_mul_f32 v[34:35], v[20:21], v[148:149] op_sel_hi:[0,1]
	v_pk_fma_f32 v[46:47], v[24:25], v[150:151], v[46:47] op_sel:[1,0,0] op_sel_hi:[1,1,1]
	v_pk_fma_f32 v[34:35], v[20:21], v[150:151], v[34:35] op_sel:[1,0,0] op_sel_hi:[1,1,1]
	v_pk_fma_f32 v[46:47], v[26:27], v[160:161], v[46:47] op_sel_hi:[0,1,1]
	v_pk_fma_f32 v[34:35], v[22:23], v[160:161], v[34:35] op_sel_hi:[0,1,1]
	v_pk_fma_f32 v[46:47], v[26:27], v[162:163], v[46:47] op_sel:[1,0,0] op_sel_hi:[1,1,1]
	v_pk_fma_f32 v[34:35], v[22:23], v[162:163], v[34:35] op_sel:[1,0,0] op_sel_hi:[1,1,1]
	v_pk_mul_f32 v[20:21], v[20:21], v[172:173]
	v_add_f32_dpp v28, v46, v34 row_half_mirror row_mask:0xf bank_mask:0xf
	v_add_f32_dpp v32, v47, v35 row_half_mirror row_mask:0xf bank_mask:0xf
	v_pk_mul_f32 v[22:23], v[22:23], v[174:175]
	v_add_f32_dpp v28, v28, v28 row_ror:8 row_mask:0xf bank_mask:0xf
	v_add_f32_dpp v32, v32, v32 row_ror:8 row_mask:0xf bank_mask:0xf
	v_pk_mul_f32 v[24:25], v[24:25], v[172:173]
	v_add_f32_dpp v28, v28, v28 quad_perm:[1,0,3,2] row_mask:0xf bank_mask:0xf
	v_add_f32_dpp v32, v32, v32 quad_perm:[1,0,3,2] row_mask:0xf bank_mask:0xf
	v_pk_mul_f32 v[26:27], v[26:27], v[174:175]
	v_add_f32_dpp v28, v28, v28 quad_perm:[2,3,0,1] row_mask:0xf bank_mask:0xf
	v_add_f32_dpp v32, v32, v32 quad_perm:[2,3,0,1] row_mask:0xf bank_mask:0xf
	v_pk_fma_f32 v[20:21], v[184:185], v[12:13], v[20:21] op_sel_hi:[1,0,1]
	v_mov_b32_dpp v30, v28 row_half_mirror row_mask:0xf bank_mask:0xf
	v_pk_fma_f32 v[22:23], v[186:187], v[12:13], v[22:23] op_sel_hi:[1,0,1]
	v_pk_fma_f32 v[24:25], v[184:185], v[14:15], v[24:25] op_sel_hi:[1,0,1]
	v_pk_fma_f32 v[26:27], v[186:187], v[14:15], v[26:27] op_sel_hi:[1,0,1]
	v_pk_fma_f32 v[20:21], v[92:93], v[28:29], v[20:21] op_sel_hi:[1,0,1] neg_lo:[0,1,0] neg_hi:[0,1,0]
	v_pk_fma_f32 v[22:23], v[94:95], v[28:29], v[22:23] op_sel_hi:[1,0,1] neg_lo:[0,1,0] neg_hi:[0,1,0]
	v_pk_fma_f32 v[24:25], v[92:93], v[30:31], v[24:25] op_sel_hi:[1,0,1] neg_lo:[0,1,0] neg_hi:[0,1,0]
	v_pk_fma_f32 v[26:27], v[94:95], v[30:31], v[26:27] op_sel_hi:[1,0,1] neg_lo:[0,1,0] neg_hi:[0,1,0]
	v_add_f32_e32 v39, v32, v13
	ds_write_b32 v102, v39 offset:1408
	ds_read_b128 v[148:151], v195 offset:3584
	ds_read_b128 v[160:163], v195 offset:11776
	ds_read_b128 v[184:187], v195 offset:19968
	ds_read_b128 v[92:95], v195 offset:36352
	ds_read_b64 v[12:13], v196 offset:7168
	ds_read_b32 v14, v36 offset:7168
	s_waitcnt lgkmcnt(14)
	v_pk_mul_f32 v[46:47], v[24:25], v[140:141] op_sel_hi:[0,1]
	v_pk_mul_f32 v[34:35], v[20:21], v[140:141] op_sel_hi:[0,1]
	v_pk_fma_f32 v[46:47], v[24:25], v[142:143], v[46:47] op_sel:[1,0,0] op_sel_hi:[1,1,1]
	v_pk_fma_f32 v[34:35], v[20:21], v[142:143], v[34:35] op_sel:[1,0,0] op_sel_hi:[1,1,1]
	v_pk_fma_f32 v[46:47], v[26:27], v[152:153], v[46:47] op_sel_hi:[0,1,1]
	v_pk_fma_f32 v[34:35], v[22:23], v[152:153], v[34:35] op_sel_hi:[0,1,1]
	v_pk_fma_f32 v[46:47], v[26:27], v[154:155], v[46:47] op_sel:[1,0,0] op_sel_hi:[1,1,1]
	v_pk_fma_f32 v[34:35], v[22:23], v[154:155], v[34:35] op_sel:[1,0,0] op_sel_hi:[1,1,1]
	v_pk_fma_f32 v[20:21], v[176:177], v[4:5], v[20:21] op_sel_hi:[1,0,1]
	v_add_f32_dpp v28, v46, v34 row_half_mirror row_mask:0xf bank_mask:0xf
	v_add_f32_dpp v32, v47, v35 row_half_mirror row_mask:0xf bank_mask:0xf
	v_pk_fma_f32 v[22:23], v[178:179], v[4:5], v[22:23] op_sel_hi:[1,0,1]
	v_add_f32_dpp v28, v28, v28 row_ror:8 row_mask:0xf bank_mask:0xf
	v_add_f32_dpp v32, v32, v32 row_ror:8 row_mask:0xf bank_mask:0xf
	v_pk_fma_f32 v[24:25], v[176:177], v[6:7], v[24:25] op_sel_hi:[1,0,1]
	v_add_f32_dpp v28, v28, v28 quad_perm:[1,0,3,2] row_mask:0xf bank_mask:0xf
	v_add_f32_dpp v32, v32, v32 quad_perm:[1,0,3,2] row_mask:0xf bank_mask:0xf
	v_pk_fma_f32 v[26:27], v[178:179], v[6:7], v[26:27] op_sel_hi:[1,0,1]
	v_add_f32_dpp v28, v28, v28 quad_perm:[2,3,0,1] row_mask:0xf bank_mask:0xf
	v_add_f32_dpp v32, v32, v32 quad_perm:[2,3,0,1] row_mask:0xf bank_mask:0xf
	v_add_f32_e32 v39, v32, v5
	v_mov_b32_dpp v30, v28 row_half_mirror row_mask:0xf bank_mask:0xf
	v_pk_fma_f32 v[20:21], v[84:85], v[28:29], v[20:21] op_sel_hi:[1,0,1] neg_lo:[0,1,0] neg_hi:[0,1,0]
	v_pk_fma_f32 v[22:23], v[86:87], v[28:29], v[22:23] op_sel_hi:[1,0,1] neg_lo:[0,1,0] neg_hi:[0,1,0]
	v_pk_fma_f32 v[24:25], v[84:85], v[30:31], v[24:25] op_sel_hi:[1,0,1] neg_lo:[0,1,0] neg_hi:[0,1,0]
	v_pk_fma_f32 v[26:27], v[86:87], v[30:31], v[26:27] op_sel_hi:[1,0,1] neg_lo:[0,1,0] neg_hi:[0,1,0]
	ds_write_b32 v102, v39 offset:1536
	ds_read_b128 v[140:143], v195 offset:3840
	ds_read_b128 v[152:155], v195 offset:12032
	ds_read_b128 v[164:167], v195 offset:28416
	ds_read_b128 v[176:179], v195 offset:20224
	ds_read_b128 v[84:87], v195 offset:36608
	ds_read_b64 v[4:5], v196 offset:7680
	ds_read_b32 v6, v36 offset:7680
	s_waitcnt lgkmcnt(15)
	v_pk_mul_f32 v[46:47], v[24:25], v[144:145] op_sel_hi:[0,1]
	v_pk_mul_f32 v[34:35], v[20:21], v[144:145] op_sel_hi:[0,1]
	v_pk_fma_f32 v[46:47], v[24:25], v[146:147], v[46:47] op_sel:[1,0,0] op_sel_hi:[1,1,1]
	v_pk_fma_f32 v[34:35], v[20:21], v[146:147], v[34:35] op_sel:[1,0,0] op_sel_hi:[1,1,1]
	v_pk_fma_f32 v[46:47], v[26:27], v[156:157], v[46:47] op_sel_hi:[0,1,1]
	v_pk_fma_f32 v[34:35], v[22:23], v[156:157], v[34:35] op_sel_hi:[0,1,1]
	v_pk_fma_f32 v[46:47], v[26:27], v[158:159], v[46:47] op_sel:[1,0,0] op_sel_hi:[1,1,1]
	v_pk_fma_f32 v[34:35], v[22:23], v[158:159], v[34:35] op_sel:[1,0,0] op_sel_hi:[1,1,1]
	v_pk_fma_f32 v[20:21], v[180:181], v[8:9], v[20:21] op_sel_hi:[1,0,1]
	v_add_f32_dpp v28, v46, v34 row_half_mirror row_mask:0xf bank_mask:0xf
	v_add_f32_dpp v32, v47, v35 row_half_mirror row_mask:0xf bank_mask:0xf
	v_pk_fma_f32 v[22:23], v[182:183], v[8:9], v[22:23] op_sel_hi:[1,0,1]
	v_add_f32_dpp v28, v28, v28 row_ror:8 row_mask:0xf bank_mask:0xf
	v_add_f32_dpp v32, v32, v32 row_ror:8 row_mask:0xf bank_mask:0xf
	v_pk_fma_f32 v[24:25], v[180:181], v[10:11], v[24:25] op_sel_hi:[1,0,1]
	v_add_f32_dpp v28, v28, v28 quad_perm:[1,0,3,2] row_mask:0xf bank_mask:0xf
	v_add_f32_dpp v32, v32, v32 quad_perm:[1,0,3,2] row_mask:0xf bank_mask:0xf
	v_pk_fma_f32 v[26:27], v[182:183], v[10:11], v[26:27] op_sel_hi:[1,0,1]
	v_add_f32_dpp v28, v28, v28 quad_perm:[2,3,0,1] row_mask:0xf bank_mask:0xf
	v_add_f32_dpp v32, v32, v32 quad_perm:[2,3,0,1] row_mask:0xf bank_mask:0xf
	v_add_f32_e32 v39, v32, v9
	v_mov_b32_dpp v30, v28 row_half_mirror row_mask:0xf bank_mask:0xf
	v_pk_fma_f32 v[20:21], v[88:89], v[28:29], v[20:21] op_sel_hi:[1,0,1] neg_lo:[0,1,0] neg_hi:[0,1,0]
	v_pk_fma_f32 v[22:23], v[90:91], v[28:29], v[22:23] op_sel_hi:[1,0,1] neg_lo:[0,1,0] neg_hi:[0,1,0]
	v_pk_fma_f32 v[24:25], v[88:89], v[30:31], v[24:25] op_sel_hi:[1,0,1] neg_lo:[0,1,0] neg_hi:[0,1,0]
	v_pk_fma_f32 v[26:27], v[90:91], v[30:31], v[26:27] op_sel_hi:[1,0,1] neg_lo:[0,1,0] neg_hi:[0,1,0]
	ds_write_b32 v102, v39 offset:1664
	ds_read_b128 v[144:147], v195 offset:4096
	ds_read_b128 v[156:159], v195 offset:12288
	ds_read_b128 v[180:183], v195 offset:20480
	ds_read_b128 v[88:91], v195 offset:36864
	ds_read_b64 v[8:9], v196 offset:8192
	ds_read_b32 v10, v36 offset:8192
	s_waitcnt lgkmcnt(15)
	v_pk_mul_f32 v[46:47], v[24:25], v[148:149] op_sel_hi:[0,1]
	v_pk_mul_f32 v[34:35], v[20:21], v[148:149] op_sel_hi:[0,1]
	v_pk_fma_f32 v[46:47], v[24:25], v[150:151], v[46:47] op_sel:[1,0,0] op_sel_hi:[1,1,1]
	v_pk_fma_f32 v[34:35], v[20:21], v[150:151], v[34:35] op_sel:[1,0,0] op_sel_hi:[1,1,1]
	v_pk_fma_f32 v[46:47], v[26:27], v[160:161], v[46:47] op_sel_hi:[0,1,1]
	v_pk_fma_f32 v[34:35], v[22:23], v[160:161], v[34:35] op_sel_hi:[0,1,1]
	v_pk_fma_f32 v[46:47], v[26:27], v[162:163], v[46:47] op_sel:[1,0,0] op_sel_hi:[1,1,1]
	v_pk_fma_f32 v[34:35], v[22:23], v[162:163], v[34:35] op_sel:[1,0,0] op_sel_hi:[1,1,1]
	v_pk_fma_f32 v[20:21], v[184:185], v[12:13], v[20:21] op_sel_hi:[1,0,1]
	v_add_f32_dpp v28, v46, v34 row_half_mirror row_mask:0xf bank_mask:0xf
	v_add_f32_dpp v32, v47, v35 row_half_mirror row_mask:0xf bank_mask:0xf
	v_pk_fma_f32 v[22:23], v[186:187], v[12:13], v[22:23] op_sel_hi:[1,0,1]
	v_add_f32_dpp v28, v28, v28 row_ror:8 row_mask:0xf bank_mask:0xf
	v_add_f32_dpp v32, v32, v32 row_ror:8 row_mask:0xf bank_mask:0xf
	v_pk_fma_f32 v[24:25], v[184:185], v[14:15], v[24:25] op_sel_hi:[1,0,1]
	v_add_f32_dpp v28, v28, v28 quad_perm:[1,0,3,2] row_mask:0xf bank_mask:0xf
	v_add_f32_dpp v32, v32, v32 quad_perm:[1,0,3,2] row_mask:0xf bank_mask:0xf
	v_pk_fma_f32 v[26:27], v[186:187], v[14:15], v[26:27] op_sel_hi:[1,0,1]
	v_add_f32_dpp v28, v28, v28 quad_perm:[2,3,0,1] row_mask:0xf bank_mask:0xf
	v_add_f32_dpp v32, v32, v32 quad_perm:[2,3,0,1] row_mask:0xf bank_mask:0xf
	v_add_f32_e32 v39, v32, v13
	v_mov_b32_dpp v30, v28 row_half_mirror row_mask:0xf bank_mask:0xf
	v_pk_fma_f32 v[20:21], v[92:93], v[28:29], v[20:21] op_sel_hi:[1,0,1] neg_lo:[0,1,0] neg_hi:[0,1,0]
	v_pk_fma_f32 v[22:23], v[94:95], v[28:29], v[22:23] op_sel_hi:[1,0,1] neg_lo:[0,1,0] neg_hi:[0,1,0]
	v_pk_fma_f32 v[24:25], v[92:93], v[30:31], v[24:25] op_sel_hi:[1,0,1] neg_lo:[0,1,0] neg_hi:[0,1,0]
	v_pk_fma_f32 v[26:27], v[94:95], v[30:31], v[26:27] op_sel_hi:[1,0,1] neg_lo:[0,1,0] neg_hi:[0,1,0]
	ds_write_b32 v102, v39 offset:1792
	ds_read_b128 v[148:151], v195 offset:4352
	ds_read_b128 v[160:163], v195 offset:12544
	ds_read_b128 v[184:187], v195 offset:20736
	ds_read_b128 v[92:95], v195 offset:37120
	ds_read_b64 v[12:13], v196 offset:8704
	ds_read_b32 v14, v36 offset:8704
	s_waitcnt lgkmcnt(14)
	v_pk_mul_f32 v[46:47], v[24:25], v[140:141] op_sel_hi:[0,1]
	v_pk_mul_f32 v[34:35], v[20:21], v[140:141] op_sel_hi:[0,1]
	v_pk_fma_f32 v[46:47], v[24:25], v[142:143], v[46:47] op_sel:[1,0,0] op_sel_hi:[1,1,1]
	v_pk_fma_f32 v[34:35], v[20:21], v[142:143], v[34:35] op_sel:[1,0,0] op_sel_hi:[1,1,1]
	v_pk_fma_f32 v[46:47], v[26:27], v[152:153], v[46:47] op_sel_hi:[0,1,1]
	v_pk_fma_f32 v[34:35], v[22:23], v[152:153], v[34:35] op_sel_hi:[0,1,1]
	v_pk_fma_f32 v[46:47], v[26:27], v[154:155], v[46:47] op_sel:[1,0,0] op_sel_hi:[1,1,1]
	v_pk_fma_f32 v[34:35], v[22:23], v[154:155], v[34:35] op_sel:[1,0,0] op_sel_hi:[1,1,1]
	v_pk_mul_f32 v[20:21], v[20:21], v[164:165]
	v_add_f32_dpp v28, v46, v34 row_half_mirror row_mask:0xf bank_mask:0xf
	v_add_f32_dpp v32, v47, v35 row_half_mirror row_mask:0xf bank_mask:0xf
	v_pk_mul_f32 v[22:23], v[22:23], v[166:167]
	v_add_f32_dpp v28, v28, v28 row_ror:8 row_mask:0xf bank_mask:0xf
	v_add_f32_dpp v32, v32, v32 row_ror:8 row_mask:0xf bank_mask:0xf
	v_pk_mul_f32 v[24:25], v[24:25], v[164:165]
	v_add_f32_dpp v28, v28, v28 quad_perm:[1,0,3,2] row_mask:0xf bank_mask:0xf
	v_add_f32_dpp v32, v32, v32 quad_perm:[1,0,3,2] row_mask:0xf bank_mask:0xf
	v_pk_mul_f32 v[26:27], v[26:27], v[166:167]
	v_add_f32_dpp v28, v28, v28 quad_perm:[2,3,0,1] row_mask:0xf bank_mask:0xf
	v_add_f32_dpp v32, v32, v32 quad_perm:[2,3,0,1] row_mask:0xf bank_mask:0xf
	v_pk_fma_f32 v[20:21], v[176:177], v[4:5], v[20:21] op_sel_hi:[1,0,1]
	v_mov_b32_dpp v30, v28 row_half_mirror row_mask:0xf bank_mask:0xf
	v_pk_fma_f32 v[22:23], v[178:179], v[4:5], v[22:23] op_sel_hi:[1,0,1]
	v_pk_fma_f32 v[24:25], v[176:177], v[6:7], v[24:25] op_sel_hi:[1,0,1]
	v_pk_fma_f32 v[26:27], v[178:179], v[6:7], v[26:27] op_sel_hi:[1,0,1]
	v_pk_fma_f32 v[20:21], v[84:85], v[28:29], v[20:21] op_sel_hi:[1,0,1] neg_lo:[0,1,0] neg_hi:[0,1,0]
	v_pk_fma_f32 v[22:23], v[86:87], v[28:29], v[22:23] op_sel_hi:[1,0,1] neg_lo:[0,1,0] neg_hi:[0,1,0]
	v_pk_fma_f32 v[24:25], v[84:85], v[30:31], v[24:25] op_sel_hi:[1,0,1] neg_lo:[0,1,0] neg_hi:[0,1,0]
	v_pk_fma_f32 v[26:27], v[86:87], v[30:31], v[26:27] op_sel_hi:[1,0,1] neg_lo:[0,1,0] neg_hi:[0,1,0]
	v_add_f32_e32 v39, v32, v5
	ds_write_b32 v102, v39 offset:1920
	ds_read_b128 v[140:143], v195 offset:4608
	ds_read_b128 v[152:155], v195 offset:12800
	ds_read_b128 v[176:179], v195 offset:20992
	ds_read_b128 v[84:87], v195 offset:37376
	ds_read_b64 v[4:5], v196 offset:9216
	ds_read_b32 v6, v36 offset:9216
	s_waitcnt lgkmcnt(14)
	v_pk_mul_f32 v[46:47], v[24:25], v[144:145] op_sel_hi:[0,1]
	v_pk_mul_f32 v[34:35], v[20:21], v[144:145] op_sel_hi:[0,1]
	v_pk_fma_f32 v[46:47], v[24:25], v[146:147], v[46:47] op_sel:[1,0,0] op_sel_hi:[1,1,1]
	v_pk_fma_f32 v[34:35], v[20:21], v[146:147], v[34:35] op_sel:[1,0,0] op_sel_hi:[1,1,1]
	v_pk_fma_f32 v[46:47], v[26:27], v[156:157], v[46:47] op_sel_hi:[0,1,1]
	v_pk_fma_f32 v[34:35], v[22:23], v[156:157], v[34:35] op_sel_hi:[0,1,1]
	v_pk_fma_f32 v[46:47], v[26:27], v[158:159], v[46:47] op_sel:[1,0,0] op_sel_hi:[1,1,1]
	v_pk_fma_f32 v[34:35], v[22:23], v[158:159], v[34:35] op_sel:[1,0,0] op_sel_hi:[1,1,1]
	v_pk_fma_f32 v[20:21], v[180:181], v[8:9], v[20:21] op_sel_hi:[1,0,1]
	v_add_f32_dpp v28, v46, v34 row_half_mirror row_mask:0xf bank_mask:0xf
	v_add_f32_dpp v32, v47, v35 row_half_mirror row_mask:0xf bank_mask:0xf
	v_pk_fma_f32 v[22:23], v[182:183], v[8:9], v[22:23] op_sel_hi:[1,0,1]
	v_add_f32_dpp v28, v28, v28 row_ror:8 row_mask:0xf bank_mask:0xf
	v_add_f32_dpp v32, v32, v32 row_ror:8 row_mask:0xf bank_mask:0xf
	v_pk_fma_f32 v[24:25], v[180:181], v[10:11], v[24:25] op_sel_hi:[1,0,1]
	v_add_f32_dpp v28, v28, v28 quad_perm:[1,0,3,2] row_mask:0xf bank_mask:0xf
	v_add_f32_dpp v32, v32, v32 quad_perm:[1,0,3,2] row_mask:0xf bank_mask:0xf
	v_pk_fma_f32 v[26:27], v[182:183], v[10:11], v[26:27] op_sel_hi:[1,0,1]
	v_add_f32_dpp v28, v28, v28 quad_perm:[2,3,0,1] row_mask:0xf bank_mask:0xf
	v_add_f32_dpp v32, v32, v32 quad_perm:[2,3,0,1] row_mask:0xf bank_mask:0xf
	v_add_f32_e32 v39, v32, v9
	v_mov_b32_dpp v30, v28 row_half_mirror row_mask:0xf bank_mask:0xf
	v_pk_fma_f32 v[20:21], v[88:89], v[28:29], v[20:21] op_sel_hi:[1,0,1] neg_lo:[0,1,0] neg_hi:[0,1,0]
	v_pk_fma_f32 v[22:23], v[90:91], v[28:29], v[22:23] op_sel_hi:[1,0,1] neg_lo:[0,1,0] neg_hi:[0,1,0]
	v_pk_fma_f32 v[24:25], v[88:89], v[30:31], v[24:25] op_sel_hi:[1,0,1] neg_lo:[0,1,0] neg_hi:[0,1,0]
	v_pk_fma_f32 v[26:27], v[90:91], v[30:31], v[26:27] op_sel_hi:[1,0,1] neg_lo:[0,1,0] neg_hi:[0,1,0]
	ds_write_b32 v102, v39 offset:2048
	ds_read_b128 v[144:147], v195 offset:4864
	ds_read_b128 v[156:159], v195 offset:13056
	ds_read_b128 v[168:171], v195 offset:29440
	ds_read_b128 v[180:183], v195 offset:21248
	ds_read_b128 v[88:91], v195 offset:37632
	ds_read_b64 v[8:9], v196 offset:9728
	ds_read_b32 v10, v36 offset:9728
	s_waitcnt lgkmcnt(15)
	v_pk_mul_f32 v[46:47], v[24:25], v[148:149] op_sel_hi:[0,1]
	v_pk_mul_f32 v[34:35], v[20:21], v[148:149] op_sel_hi:[0,1]
	v_pk_fma_f32 v[46:47], v[24:25], v[150:151], v[46:47] op_sel:[1,0,0] op_sel_hi:[1,1,1]
	v_pk_fma_f32 v[34:35], v[20:21], v[150:151], v[34:35] op_sel:[1,0,0] op_sel_hi:[1,1,1]
	v_pk_fma_f32 v[46:47], v[26:27], v[160:161], v[46:47] op_sel_hi:[0,1,1]
	v_pk_fma_f32 v[34:35], v[22:23], v[160:161], v[34:35] op_sel_hi:[0,1,1]
	v_pk_fma_f32 v[46:47], v[26:27], v[162:163], v[46:47] op_sel:[1,0,0] op_sel_hi:[1,1,1]
	v_pk_fma_f32 v[34:35], v[22:23], v[162:163], v[34:35] op_sel:[1,0,0] op_sel_hi:[1,1,1]
	v_pk_fma_f32 v[20:21], v[184:185], v[12:13], v[20:21] op_sel_hi:[1,0,1]
	v_add_f32_dpp v28, v46, v34 row_half_mirror row_mask:0xf bank_mask:0xf
	v_add_f32_dpp v32, v47, v35 row_half_mirror row_mask:0xf bank_mask:0xf
	v_pk_fma_f32 v[22:23], v[186:187], v[12:13], v[22:23] op_sel_hi:[1,0,1]
	v_add_f32_dpp v28, v28, v28 row_ror:8 row_mask:0xf bank_mask:0xf
	v_add_f32_dpp v32, v32, v32 row_ror:8 row_mask:0xf bank_mask:0xf
	v_pk_fma_f32 v[24:25], v[184:185], v[14:15], v[24:25] op_sel_hi:[1,0,1]
	v_add_f32_dpp v28, v28, v28 quad_perm:[1,0,3,2] row_mask:0xf bank_mask:0xf
	v_add_f32_dpp v32, v32, v32 quad_perm:[1,0,3,2] row_mask:0xf bank_mask:0xf
	v_pk_fma_f32 v[26:27], v[186:187], v[14:15], v[26:27] op_sel_hi:[1,0,1]
	v_add_f32_dpp v28, v28, v28 quad_perm:[2,3,0,1] row_mask:0xf bank_mask:0xf
	v_add_f32_dpp v32, v32, v32 quad_perm:[2,3,0,1] row_mask:0xf bank_mask:0xf
	v_add_f32_e32 v39, v32, v13
	v_mov_b32_dpp v30, v28 row_half_mirror row_mask:0xf bank_mask:0xf
	v_pk_fma_f32 v[20:21], v[92:93], v[28:29], v[20:21] op_sel_hi:[1,0,1] neg_lo:[0,1,0] neg_hi:[0,1,0]
	v_pk_fma_f32 v[22:23], v[94:95], v[28:29], v[22:23] op_sel_hi:[1,0,1] neg_lo:[0,1,0] neg_hi:[0,1,0]
	v_pk_fma_f32 v[24:25], v[92:93], v[30:31], v[24:25] op_sel_hi:[1,0,1] neg_lo:[0,1,0] neg_hi:[0,1,0]
	v_pk_fma_f32 v[26:27], v[94:95], v[30:31], v[26:27] op_sel_hi:[1,0,1] neg_lo:[0,1,0] neg_hi:[0,1,0]
	ds_write_b32 v102, v39 offset:2176
	ds_read_b128 v[148:151], v195 offset:5120
	ds_read_b128 v[160:163], v195 offset:13312
	ds_read_b128 v[184:187], v195 offset:21504
	ds_read_b128 v[92:95], v195 offset:37888
	ds_read_b64 v[12:13], v196 offset:10240
	ds_read_b32 v14, v36 offset:10240
	s_waitcnt lgkmcnt(15)
	v_pk_mul_f32 v[46:47], v[24:25], v[140:141] op_sel_hi:[0,1]
	v_pk_mul_f32 v[34:35], v[20:21], v[140:141] op_sel_hi:[0,1]
	v_pk_fma_f32 v[46:47], v[24:25], v[142:143], v[46:47] op_sel:[1,0,0] op_sel_hi:[1,1,1]
	v_pk_fma_f32 v[34:35], v[20:21], v[142:143], v[34:35] op_sel:[1,0,0] op_sel_hi:[1,1,1]
	v_pk_fma_f32 v[46:47], v[26:27], v[152:153], v[46:47] op_sel_hi:[0,1,1]
	v_pk_fma_f32 v[34:35], v[22:23], v[152:153], v[34:35] op_sel_hi:[0,1,1]
	v_pk_fma_f32 v[46:47], v[26:27], v[154:155], v[46:47] op_sel:[1,0,0] op_sel_hi:[1,1,1]
	v_pk_fma_f32 v[34:35], v[22:23], v[154:155], v[34:35] op_sel:[1,0,0] op_sel_hi:[1,1,1]
	v_pk_fma_f32 v[20:21], v[176:177], v[4:5], v[20:21] op_sel_hi:[1,0,1]
	v_add_f32_dpp v28, v46, v34 row_half_mirror row_mask:0xf bank_mask:0xf
	v_add_f32_dpp v32, v47, v35 row_half_mirror row_mask:0xf bank_mask:0xf
	v_pk_fma_f32 v[22:23], v[178:179], v[4:5], v[22:23] op_sel_hi:[1,0,1]
	v_add_f32_dpp v28, v28, v28 row_ror:8 row_mask:0xf bank_mask:0xf
	v_add_f32_dpp v32, v32, v32 row_ror:8 row_mask:0xf bank_mask:0xf
	v_pk_fma_f32 v[24:25], v[176:177], v[6:7], v[24:25] op_sel_hi:[1,0,1]
	v_add_f32_dpp v28, v28, v28 quad_perm:[1,0,3,2] row_mask:0xf bank_mask:0xf
	v_add_f32_dpp v32, v32, v32 quad_perm:[1,0,3,2] row_mask:0xf bank_mask:0xf
	v_pk_fma_f32 v[26:27], v[178:179], v[6:7], v[26:27] op_sel_hi:[1,0,1]
	v_add_f32_dpp v28, v28, v28 quad_perm:[2,3,0,1] row_mask:0xf bank_mask:0xf
	v_add_f32_dpp v32, v32, v32 quad_perm:[2,3,0,1] row_mask:0xf bank_mask:0xf
	v_add_f32_e32 v39, v32, v5
	v_mov_b32_dpp v30, v28 row_half_mirror row_mask:0xf bank_mask:0xf
	v_pk_fma_f32 v[20:21], v[84:85], v[28:29], v[20:21] op_sel_hi:[1,0,1] neg_lo:[0,1,0] neg_hi:[0,1,0]
	v_pk_fma_f32 v[22:23], v[86:87], v[28:29], v[22:23] op_sel_hi:[1,0,1] neg_lo:[0,1,0] neg_hi:[0,1,0]
	v_pk_fma_f32 v[24:25], v[84:85], v[30:31], v[24:25] op_sel_hi:[1,0,1] neg_lo:[0,1,0] neg_hi:[0,1,0]
	v_pk_fma_f32 v[26:27], v[86:87], v[30:31], v[26:27] op_sel_hi:[1,0,1] neg_lo:[0,1,0] neg_hi:[0,1,0]
	ds_write_b32 v102, v39 offset:2304
	ds_read_b128 v[140:143], v195 offset:5376
	ds_read_b128 v[152:155], v195 offset:13568
	ds_read_b128 v[176:179], v195 offset:21760
	ds_read_b128 v[84:87], v195 offset:38144
	ds_read_b64 v[4:5], v196 offset:10752
	ds_read_b32 v6, v36 offset:10752
	s_waitcnt lgkmcnt(14)
	v_pk_mul_f32 v[46:47], v[24:25], v[144:145] op_sel_hi:[0,1]
	v_pk_mul_f32 v[34:35], v[20:21], v[144:145] op_sel_hi:[0,1]
	v_pk_fma_f32 v[46:47], v[24:25], v[146:147], v[46:47] op_sel:[1,0,0] op_sel_hi:[1,1,1]
	v_pk_fma_f32 v[34:35], v[20:21], v[146:147], v[34:35] op_sel:[1,0,0] op_sel_hi:[1,1,1]
	v_pk_fma_f32 v[46:47], v[26:27], v[156:157], v[46:47] op_sel_hi:[0,1,1]
	v_pk_fma_f32 v[34:35], v[22:23], v[156:157], v[34:35] op_sel_hi:[0,1,1]
	v_pk_fma_f32 v[46:47], v[26:27], v[158:159], v[46:47] op_sel:[1,0,0] op_sel_hi:[1,1,1]
	v_pk_fma_f32 v[34:35], v[22:23], v[158:159], v[34:35] op_sel:[1,0,0] op_sel_hi:[1,1,1]
	v_pk_mul_f32 v[20:21], v[20:21], v[168:169]
	v_add_f32_dpp v28, v46, v34 row_half_mirror row_mask:0xf bank_mask:0xf
	v_add_f32_dpp v32, v47, v35 row_half_mirror row_mask:0xf bank_mask:0xf
	v_pk_mul_f32 v[22:23], v[22:23], v[170:171]
	v_add_f32_dpp v28, v28, v28 row_ror:8 row_mask:0xf bank_mask:0xf
	v_add_f32_dpp v32, v32, v32 row_ror:8 row_mask:0xf bank_mask:0xf
	v_pk_mul_f32 v[24:25], v[24:25], v[168:169]
	v_add_f32_dpp v28, v28, v28 quad_perm:[1,0,3,2] row_mask:0xf bank_mask:0xf
	v_add_f32_dpp v32, v32, v32 quad_perm:[1,0,3,2] row_mask:0xf bank_mask:0xf
	v_pk_mul_f32 v[26:27], v[26:27], v[170:171]
	v_add_f32_dpp v28, v28, v28 quad_perm:[2,3,0,1] row_mask:0xf bank_mask:0xf
	v_add_f32_dpp v32, v32, v32 quad_perm:[2,3,0,1] row_mask:0xf bank_mask:0xf
	v_pk_fma_f32 v[20:21], v[180:181], v[8:9], v[20:21] op_sel_hi:[1,0,1]
	v_mov_b32_dpp v30, v28 row_half_mirror row_mask:0xf bank_mask:0xf
	v_pk_fma_f32 v[22:23], v[182:183], v[8:9], v[22:23] op_sel_hi:[1,0,1]
	v_pk_fma_f32 v[24:25], v[180:181], v[10:11], v[24:25] op_sel_hi:[1,0,1]
	v_pk_fma_f32 v[26:27], v[182:183], v[10:11], v[26:27] op_sel_hi:[1,0,1]
	v_pk_fma_f32 v[20:21], v[88:89], v[28:29], v[20:21] op_sel_hi:[1,0,1] neg_lo:[0,1,0] neg_hi:[0,1,0]
	v_pk_fma_f32 v[22:23], v[90:91], v[28:29], v[22:23] op_sel_hi:[1,0,1] neg_lo:[0,1,0] neg_hi:[0,1,0]
	v_pk_fma_f32 v[24:25], v[88:89], v[30:31], v[24:25] op_sel_hi:[1,0,1] neg_lo:[0,1,0] neg_hi:[0,1,0]
	v_pk_fma_f32 v[26:27], v[90:91], v[30:31], v[26:27] op_sel_hi:[1,0,1] neg_lo:[0,1,0] neg_hi:[0,1,0]
	v_add_f32_e32 v39, v32, v9
	ds_write_b32 v102, v39 offset:2432
	ds_read_b128 v[144:147], v195 offset:5632
	ds_read_b128 v[156:159], v195 offset:13824
	ds_read_b128 v[180:183], v195 offset:22016
	ds_read_b128 v[88:91], v195 offset:38400
	ds_read_b64 v[8:9], v196 offset:11264
	ds_read_b32 v10, v36 offset:11264
	s_waitcnt lgkmcnt(14)
	v_pk_mul_f32 v[46:47], v[24:25], v[148:149] op_sel_hi:[0,1]
	v_pk_mul_f32 v[34:35], v[20:21], v[148:149] op_sel_hi:[0,1]
	v_pk_fma_f32 v[46:47], v[24:25], v[150:151], v[46:47] op_sel:[1,0,0] op_sel_hi:[1,1,1]
	v_pk_fma_f32 v[34:35], v[20:21], v[150:151], v[34:35] op_sel:[1,0,0] op_sel_hi:[1,1,1]
	v_pk_fma_f32 v[46:47], v[26:27], v[160:161], v[46:47] op_sel_hi:[0,1,1]
	v_pk_fma_f32 v[34:35], v[22:23], v[160:161], v[34:35] op_sel_hi:[0,1,1]
	v_pk_fma_f32 v[46:47], v[26:27], v[162:163], v[46:47] op_sel:[1,0,0] op_sel_hi:[1,1,1]
	v_pk_fma_f32 v[34:35], v[22:23], v[162:163], v[34:35] op_sel:[1,0,0] op_sel_hi:[1,1,1]
	v_pk_fma_f32 v[20:21], v[184:185], v[12:13], v[20:21] op_sel_hi:[1,0,1]
	v_add_f32_dpp v28, v46, v34 row_half_mirror row_mask:0xf bank_mask:0xf
	v_add_f32_dpp v32, v47, v35 row_half_mirror row_mask:0xf bank_mask:0xf
	v_pk_fma_f32 v[22:23], v[186:187], v[12:13], v[22:23] op_sel_hi:[1,0,1]
	v_add_f32_dpp v28, v28, v28 row_ror:8 row_mask:0xf bank_mask:0xf
	v_add_f32_dpp v32, v32, v32 row_ror:8 row_mask:0xf bank_mask:0xf
	v_pk_fma_f32 v[24:25], v[184:185], v[14:15], v[24:25] op_sel_hi:[1,0,1]
	v_add_f32_dpp v28, v28, v28 quad_perm:[1,0,3,2] row_mask:0xf bank_mask:0xf
	v_add_f32_dpp v32, v32, v32 quad_perm:[1,0,3,2] row_mask:0xf bank_mask:0xf
	v_pk_fma_f32 v[26:27], v[186:187], v[14:15], v[26:27] op_sel_hi:[1,0,1]
	v_add_f32_dpp v28, v28, v28 quad_perm:[2,3,0,1] row_mask:0xf bank_mask:0xf
	v_add_f32_dpp v32, v32, v32 quad_perm:[2,3,0,1] row_mask:0xf bank_mask:0xf
	v_add_f32_e32 v39, v32, v13
	v_mov_b32_dpp v30, v28 row_half_mirror row_mask:0xf bank_mask:0xf
	v_pk_fma_f32 v[20:21], v[92:93], v[28:29], v[20:21] op_sel_hi:[1,0,1] neg_lo:[0,1,0] neg_hi:[0,1,0]
	v_pk_fma_f32 v[22:23], v[94:95], v[28:29], v[22:23] op_sel_hi:[1,0,1] neg_lo:[0,1,0] neg_hi:[0,1,0]
	v_pk_fma_f32 v[24:25], v[92:93], v[30:31], v[24:25] op_sel_hi:[1,0,1] neg_lo:[0,1,0] neg_hi:[0,1,0]
	v_pk_fma_f32 v[26:27], v[94:95], v[30:31], v[26:27] op_sel_hi:[1,0,1] neg_lo:[0,1,0] neg_hi:[0,1,0]
	ds_write_b32 v102, v39 offset:2560
	ds_read_b128 v[148:151], v195 offset:5888
	ds_read_b128 v[160:163], v195 offset:14080
	ds_read_b128 v[172:175], v195 offset:30464
	ds_read_b128 v[184:187], v195 offset:22272
	ds_read_b128 v[92:95], v195 offset:38656
	ds_read_b64 v[12:13], v196 offset:11776
	ds_read_b32 v14, v36 offset:11776
	s_waitcnt lgkmcnt(15)
	v_pk_mul_f32 v[46:47], v[24:25], v[140:141] op_sel_hi:[0,1]
	v_pk_mul_f32 v[34:35], v[20:21], v[140:141] op_sel_hi:[0,1]
	v_pk_fma_f32 v[46:47], v[24:25], v[142:143], v[46:47] op_sel:[1,0,0] op_sel_hi:[1,1,1]
	v_pk_fma_f32 v[34:35], v[20:21], v[142:143], v[34:35] op_sel:[1,0,0] op_sel_hi:[1,1,1]
	v_pk_fma_f32 v[46:47], v[26:27], v[152:153], v[46:47] op_sel_hi:[0,1,1]
	v_pk_fma_f32 v[34:35], v[22:23], v[152:153], v[34:35] op_sel_hi:[0,1,1]
	v_pk_fma_f32 v[46:47], v[26:27], v[154:155], v[46:47] op_sel:[1,0,0] op_sel_hi:[1,1,1]
	v_pk_fma_f32 v[34:35], v[22:23], v[154:155], v[34:35] op_sel:[1,0,0] op_sel_hi:[1,1,1]
	v_pk_fma_f32 v[20:21], v[176:177], v[4:5], v[20:21] op_sel_hi:[1,0,1]
	v_add_f32_dpp v28, v46, v34 row_half_mirror row_mask:0xf bank_mask:0xf
	v_add_f32_dpp v32, v47, v35 row_half_mirror row_mask:0xf bank_mask:0xf
	v_pk_fma_f32 v[22:23], v[178:179], v[4:5], v[22:23] op_sel_hi:[1,0,1]
	v_add_f32_dpp v28, v28, v28 row_ror:8 row_mask:0xf bank_mask:0xf
	v_add_f32_dpp v32, v32, v32 row_ror:8 row_mask:0xf bank_mask:0xf
	v_pk_fma_f32 v[24:25], v[176:177], v[6:7], v[24:25] op_sel_hi:[1,0,1]
	v_add_f32_dpp v28, v28, v28 quad_perm:[1,0,3,2] row_mask:0xf bank_mask:0xf
	v_add_f32_dpp v32, v32, v32 quad_perm:[1,0,3,2] row_mask:0xf bank_mask:0xf
	v_pk_fma_f32 v[26:27], v[178:179], v[6:7], v[26:27] op_sel_hi:[1,0,1]
	v_add_f32_dpp v28, v28, v28 quad_perm:[2,3,0,1] row_mask:0xf bank_mask:0xf
	v_add_f32_dpp v32, v32, v32 quad_perm:[2,3,0,1] row_mask:0xf bank_mask:0xf
	v_add_f32_e32 v39, v32, v5
	v_mov_b32_dpp v30, v28 row_half_mirror row_mask:0xf bank_mask:0xf
	v_pk_fma_f32 v[20:21], v[84:85], v[28:29], v[20:21] op_sel_hi:[1,0,1] neg_lo:[0,1,0] neg_hi:[0,1,0]
	v_pk_fma_f32 v[22:23], v[86:87], v[28:29], v[22:23] op_sel_hi:[1,0,1] neg_lo:[0,1,0] neg_hi:[0,1,0]
	v_pk_fma_f32 v[24:25], v[84:85], v[30:31], v[24:25] op_sel_hi:[1,0,1] neg_lo:[0,1,0] neg_hi:[0,1,0]
	v_pk_fma_f32 v[26:27], v[86:87], v[30:31], v[26:27] op_sel_hi:[1,0,1] neg_lo:[0,1,0] neg_hi:[0,1,0]
	ds_write_b32 v102, v39 offset:2688
	ds_read_b128 v[140:143], v195 offset:6144
	ds_read_b128 v[152:155], v195 offset:14336
	ds_read_b128 v[176:179], v195 offset:22528
	ds_read_b128 v[84:87], v195 offset:38912
	ds_read_b64 v[4:5], v196 offset:12288
	ds_read_b32 v6, v36 offset:12288
	s_waitcnt lgkmcnt(15)
	v_pk_mul_f32 v[46:47], v[24:25], v[144:145] op_sel_hi:[0,1]
	v_pk_mul_f32 v[34:35], v[20:21], v[144:145] op_sel_hi:[0,1]
	v_pk_fma_f32 v[46:47], v[24:25], v[146:147], v[46:47] op_sel:[1,0,0] op_sel_hi:[1,1,1]
	v_pk_fma_f32 v[34:35], v[20:21], v[146:147], v[34:35] op_sel:[1,0,0] op_sel_hi:[1,1,1]
	v_pk_fma_f32 v[46:47], v[26:27], v[156:157], v[46:47] op_sel_hi:[0,1,1]
	v_pk_fma_f32 v[34:35], v[22:23], v[156:157], v[34:35] op_sel_hi:[0,1,1]
	v_pk_fma_f32 v[46:47], v[26:27], v[158:159], v[46:47] op_sel:[1,0,0] op_sel_hi:[1,1,1]
	v_pk_fma_f32 v[34:35], v[22:23], v[158:159], v[34:35] op_sel:[1,0,0] op_sel_hi:[1,1,1]
	v_pk_fma_f32 v[20:21], v[180:181], v[8:9], v[20:21] op_sel_hi:[1,0,1]
	v_add_f32_dpp v28, v46, v34 row_half_mirror row_mask:0xf bank_mask:0xf
	v_add_f32_dpp v32, v47, v35 row_half_mirror row_mask:0xf bank_mask:0xf
	v_pk_fma_f32 v[22:23], v[182:183], v[8:9], v[22:23] op_sel_hi:[1,0,1]
	v_add_f32_dpp v28, v28, v28 row_ror:8 row_mask:0xf bank_mask:0xf
	v_add_f32_dpp v32, v32, v32 row_ror:8 row_mask:0xf bank_mask:0xf
	v_pk_fma_f32 v[24:25], v[180:181], v[10:11], v[24:25] op_sel_hi:[1,0,1]
	v_add_f32_dpp v28, v28, v28 quad_perm:[1,0,3,2] row_mask:0xf bank_mask:0xf
	v_add_f32_dpp v32, v32, v32 quad_perm:[1,0,3,2] row_mask:0xf bank_mask:0xf
	v_pk_fma_f32 v[26:27], v[182:183], v[10:11], v[26:27] op_sel_hi:[1,0,1]
	v_add_f32_dpp v28, v28, v28 quad_perm:[2,3,0,1] row_mask:0xf bank_mask:0xf
	v_add_f32_dpp v32, v32, v32 quad_perm:[2,3,0,1] row_mask:0xf bank_mask:0xf
	v_add_f32_e32 v39, v32, v9
	v_mov_b32_dpp v30, v28 row_half_mirror row_mask:0xf bank_mask:0xf
	v_pk_fma_f32 v[20:21], v[88:89], v[28:29], v[20:21] op_sel_hi:[1,0,1] neg_lo:[0,1,0] neg_hi:[0,1,0]
	v_pk_fma_f32 v[22:23], v[90:91], v[28:29], v[22:23] op_sel_hi:[1,0,1] neg_lo:[0,1,0] neg_hi:[0,1,0]
	v_pk_fma_f32 v[24:25], v[88:89], v[30:31], v[24:25] op_sel_hi:[1,0,1] neg_lo:[0,1,0] neg_hi:[0,1,0]
	v_pk_fma_f32 v[26:27], v[90:91], v[30:31], v[26:27] op_sel_hi:[1,0,1] neg_lo:[0,1,0] neg_hi:[0,1,0]
	ds_write_b32 v102, v39 offset:2816
	ds_read_b128 v[144:147], v195 offset:6400
	ds_read_b128 v[156:159], v195 offset:14592
	ds_read_b128 v[180:183], v195 offset:22784
	ds_read_b128 v[88:91], v195 offset:39168
	ds_read_b64 v[8:9], v196 offset:12800
	ds_read_b32 v10, v36 offset:12800
	s_waitcnt lgkmcnt(14)
	v_pk_mul_f32 v[46:47], v[24:25], v[148:149] op_sel_hi:[0,1]
	v_pk_mul_f32 v[34:35], v[20:21], v[148:149] op_sel_hi:[0,1]
	v_pk_fma_f32 v[46:47], v[24:25], v[150:151], v[46:47] op_sel:[1,0,0] op_sel_hi:[1,1,1]
	v_pk_fma_f32 v[34:35], v[20:21], v[150:151], v[34:35] op_sel:[1,0,0] op_sel_hi:[1,1,1]
	v_pk_fma_f32 v[46:47], v[26:27], v[160:161], v[46:47] op_sel_hi:[0,1,1]
	v_pk_fma_f32 v[34:35], v[22:23], v[160:161], v[34:35] op_sel_hi:[0,1,1]
	v_pk_fma_f32 v[46:47], v[26:27], v[162:163], v[46:47] op_sel:[1,0,0] op_sel_hi:[1,1,1]
	v_pk_fma_f32 v[34:35], v[22:23], v[162:163], v[34:35] op_sel:[1,0,0] op_sel_hi:[1,1,1]
	v_pk_mul_f32 v[20:21], v[20:21], v[172:173]
	v_add_f32_dpp v28, v46, v34 row_half_mirror row_mask:0xf bank_mask:0xf
	v_add_f32_dpp v32, v47, v35 row_half_mirror row_mask:0xf bank_mask:0xf
	v_pk_mul_f32 v[22:23], v[22:23], v[174:175]
	v_add_f32_dpp v28, v28, v28 row_ror:8 row_mask:0xf bank_mask:0xf
	v_add_f32_dpp v32, v32, v32 row_ror:8 row_mask:0xf bank_mask:0xf
	v_pk_mul_f32 v[24:25], v[24:25], v[172:173]
	v_add_f32_dpp v28, v28, v28 quad_perm:[1,0,3,2] row_mask:0xf bank_mask:0xf
	v_add_f32_dpp v32, v32, v32 quad_perm:[1,0,3,2] row_mask:0xf bank_mask:0xf
	v_pk_mul_f32 v[26:27], v[26:27], v[174:175]
	v_add_f32_dpp v28, v28, v28 quad_perm:[2,3,0,1] row_mask:0xf bank_mask:0xf
	v_add_f32_dpp v32, v32, v32 quad_perm:[2,3,0,1] row_mask:0xf bank_mask:0xf
	v_pk_fma_f32 v[20:21], v[184:185], v[12:13], v[20:21] op_sel_hi:[1,0,1]
	v_mov_b32_dpp v30, v28 row_half_mirror row_mask:0xf bank_mask:0xf
	v_pk_fma_f32 v[22:23], v[186:187], v[12:13], v[22:23] op_sel_hi:[1,0,1]
	v_pk_fma_f32 v[24:25], v[184:185], v[14:15], v[24:25] op_sel_hi:[1,0,1]
	v_pk_fma_f32 v[26:27], v[186:187], v[14:15], v[26:27] op_sel_hi:[1,0,1]
	v_pk_fma_f32 v[20:21], v[92:93], v[28:29], v[20:21] op_sel_hi:[1,0,1] neg_lo:[0,1,0] neg_hi:[0,1,0]
	v_pk_fma_f32 v[22:23], v[94:95], v[28:29], v[22:23] op_sel_hi:[1,0,1] neg_lo:[0,1,0] neg_hi:[0,1,0]
	v_pk_fma_f32 v[24:25], v[92:93], v[30:31], v[24:25] op_sel_hi:[1,0,1] neg_lo:[0,1,0] neg_hi:[0,1,0]
	v_pk_fma_f32 v[26:27], v[94:95], v[30:31], v[26:27] op_sel_hi:[1,0,1] neg_lo:[0,1,0] neg_hi:[0,1,0]
	v_add_f32_e32 v39, v32, v13
	ds_write_b32 v102, v39 offset:2944
	ds_read_b128 v[148:151], v195 offset:6656
	ds_read_b128 v[160:163], v195 offset:14848
	ds_read_b128 v[184:187], v195 offset:23040
	ds_read_b128 v[92:95], v195 offset:39424
	ds_read_b64 v[12:13], v196 offset:13312
	ds_read_b32 v14, v36 offset:13312
	s_waitcnt lgkmcnt(14)
	v_pk_mul_f32 v[46:47], v[24:25], v[140:141] op_sel_hi:[0,1]
	v_pk_mul_f32 v[34:35], v[20:21], v[140:141] op_sel_hi:[0,1]
	v_pk_fma_f32 v[46:47], v[24:25], v[142:143], v[46:47] op_sel:[1,0,0] op_sel_hi:[1,1,1]
	v_pk_fma_f32 v[34:35], v[20:21], v[142:143], v[34:35] op_sel:[1,0,0] op_sel_hi:[1,1,1]
	v_pk_fma_f32 v[46:47], v[26:27], v[152:153], v[46:47] op_sel_hi:[0,1,1]
	v_pk_fma_f32 v[34:35], v[22:23], v[152:153], v[34:35] op_sel_hi:[0,1,1]
	v_pk_fma_f32 v[46:47], v[26:27], v[154:155], v[46:47] op_sel:[1,0,0] op_sel_hi:[1,1,1]
	v_pk_fma_f32 v[34:35], v[22:23], v[154:155], v[34:35] op_sel:[1,0,0] op_sel_hi:[1,1,1]
	v_pk_fma_f32 v[20:21], v[176:177], v[4:5], v[20:21] op_sel_hi:[1,0,1]
	v_add_f32_dpp v28, v46, v34 row_half_mirror row_mask:0xf bank_mask:0xf
	v_add_f32_dpp v32, v47, v35 row_half_mirror row_mask:0xf bank_mask:0xf
	v_pk_fma_f32 v[22:23], v[178:179], v[4:5], v[22:23] op_sel_hi:[1,0,1]
	v_add_f32_dpp v28, v28, v28 row_ror:8 row_mask:0xf bank_mask:0xf
	v_add_f32_dpp v32, v32, v32 row_ror:8 row_mask:0xf bank_mask:0xf
	v_pk_fma_f32 v[24:25], v[176:177], v[6:7], v[24:25] op_sel_hi:[1,0,1]
	v_add_f32_dpp v28, v28, v28 quad_perm:[1,0,3,2] row_mask:0xf bank_mask:0xf
	v_add_f32_dpp v32, v32, v32 quad_perm:[1,0,3,2] row_mask:0xf bank_mask:0xf
	v_pk_fma_f32 v[26:27], v[178:179], v[6:7], v[26:27] op_sel_hi:[1,0,1]
	v_add_f32_dpp v28, v28, v28 quad_perm:[2,3,0,1] row_mask:0xf bank_mask:0xf
	v_add_f32_dpp v32, v32, v32 quad_perm:[2,3,0,1] row_mask:0xf bank_mask:0xf
	v_add_f32_e32 v39, v32, v5
	v_mov_b32_dpp v30, v28 row_half_mirror row_mask:0xf bank_mask:0xf
	v_pk_fma_f32 v[20:21], v[84:85], v[28:29], v[20:21] op_sel_hi:[1,0,1] neg_lo:[0,1,0] neg_hi:[0,1,0]
	v_pk_fma_f32 v[22:23], v[86:87], v[28:29], v[22:23] op_sel_hi:[1,0,1] neg_lo:[0,1,0] neg_hi:[0,1,0]
	v_pk_fma_f32 v[24:25], v[84:85], v[30:31], v[24:25] op_sel_hi:[1,0,1] neg_lo:[0,1,0] neg_hi:[0,1,0]
	v_pk_fma_f32 v[26:27], v[86:87], v[30:31], v[26:27] op_sel_hi:[1,0,1] neg_lo:[0,1,0] neg_hi:[0,1,0]
	ds_write_b32 v102, v39 offset:3072
	ds_read_b128 v[140:143], v195 offset:6912
	ds_read_b128 v[152:155], v195 offset:15104
	ds_read_b128 v[164:167], v195 offset:31488
	ds_read_b128 v[176:179], v195 offset:23296
	ds_read_b128 v[84:87], v195 offset:39680
	ds_read_b64 v[4:5], v196 offset:13824
	ds_read_b32 v6, v36 offset:13824
	s_waitcnt lgkmcnt(15)
	v_pk_mul_f32 v[46:47], v[24:25], v[144:145] op_sel_hi:[0,1]
	v_pk_mul_f32 v[34:35], v[20:21], v[144:145] op_sel_hi:[0,1]
	v_pk_fma_f32 v[46:47], v[24:25], v[146:147], v[46:47] op_sel:[1,0,0] op_sel_hi:[1,1,1]
	v_pk_fma_f32 v[34:35], v[20:21], v[146:147], v[34:35] op_sel:[1,0,0] op_sel_hi:[1,1,1]
	v_pk_fma_f32 v[46:47], v[26:27], v[156:157], v[46:47] op_sel_hi:[0,1,1]
	v_pk_fma_f32 v[34:35], v[22:23], v[156:157], v[34:35] op_sel_hi:[0,1,1]
	v_pk_fma_f32 v[46:47], v[26:27], v[158:159], v[46:47] op_sel:[1,0,0] op_sel_hi:[1,1,1]
	v_pk_fma_f32 v[34:35], v[22:23], v[158:159], v[34:35] op_sel:[1,0,0] op_sel_hi:[1,1,1]
	v_pk_fma_f32 v[20:21], v[180:181], v[8:9], v[20:21] op_sel_hi:[1,0,1]
	v_add_f32_dpp v28, v46, v34 row_half_mirror row_mask:0xf bank_mask:0xf
	v_add_f32_dpp v32, v47, v35 row_half_mirror row_mask:0xf bank_mask:0xf
	v_pk_fma_f32 v[22:23], v[182:183], v[8:9], v[22:23] op_sel_hi:[1,0,1]
	v_add_f32_dpp v28, v28, v28 row_ror:8 row_mask:0xf bank_mask:0xf
	v_add_f32_dpp v32, v32, v32 row_ror:8 row_mask:0xf bank_mask:0xf
	v_pk_fma_f32 v[24:25], v[180:181], v[10:11], v[24:25] op_sel_hi:[1,0,1]
	v_add_f32_dpp v28, v28, v28 quad_perm:[1,0,3,2] row_mask:0xf bank_mask:0xf
	v_add_f32_dpp v32, v32, v32 quad_perm:[1,0,3,2] row_mask:0xf bank_mask:0xf
	v_pk_fma_f32 v[26:27], v[182:183], v[10:11], v[26:27] op_sel_hi:[1,0,1]
	v_add_f32_dpp v28, v28, v28 quad_perm:[2,3,0,1] row_mask:0xf bank_mask:0xf
	v_add_f32_dpp v32, v32, v32 quad_perm:[2,3,0,1] row_mask:0xf bank_mask:0xf
	v_add_f32_e32 v39, v32, v9
	v_mov_b32_dpp v30, v28 row_half_mirror row_mask:0xf bank_mask:0xf
	v_pk_fma_f32 v[20:21], v[88:89], v[28:29], v[20:21] op_sel_hi:[1,0,1] neg_lo:[0,1,0] neg_hi:[0,1,0]
	v_pk_fma_f32 v[22:23], v[90:91], v[28:29], v[22:23] op_sel_hi:[1,0,1] neg_lo:[0,1,0] neg_hi:[0,1,0]
	v_pk_fma_f32 v[24:25], v[88:89], v[30:31], v[24:25] op_sel_hi:[1,0,1] neg_lo:[0,1,0] neg_hi:[0,1,0]
	v_pk_fma_f32 v[26:27], v[90:91], v[30:31], v[26:27] op_sel_hi:[1,0,1] neg_lo:[0,1,0] neg_hi:[0,1,0]
	ds_write_b32 v102, v39 offset:3200
	ds_read_b128 v[144:147], v195 offset:7168
	ds_read_b128 v[156:159], v195 offset:15360
	ds_read_b128 v[180:183], v195 offset:23552
	ds_read_b128 v[88:91], v195 offset:39936
	ds_read_b64 v[8:9], v196 offset:14336
	ds_read_b32 v10, v36 offset:14336
	s_waitcnt lgkmcnt(15)
	v_pk_mul_f32 v[46:47], v[24:25], v[148:149] op_sel_hi:[0,1]
	v_pk_mul_f32 v[34:35], v[20:21], v[148:149] op_sel_hi:[0,1]
	v_pk_fma_f32 v[46:47], v[24:25], v[150:151], v[46:47] op_sel:[1,0,0] op_sel_hi:[1,1,1]
	v_pk_fma_f32 v[34:35], v[20:21], v[150:151], v[34:35] op_sel:[1,0,0] op_sel_hi:[1,1,1]
	v_pk_fma_f32 v[46:47], v[26:27], v[160:161], v[46:47] op_sel_hi:[0,1,1]
	v_pk_fma_f32 v[34:35], v[22:23], v[160:161], v[34:35] op_sel_hi:[0,1,1]
	v_pk_fma_f32 v[46:47], v[26:27], v[162:163], v[46:47] op_sel:[1,0,0] op_sel_hi:[1,1,1]
	v_pk_fma_f32 v[34:35], v[22:23], v[162:163], v[34:35] op_sel:[1,0,0] op_sel_hi:[1,1,1]
	v_pk_fma_f32 v[20:21], v[184:185], v[12:13], v[20:21] op_sel_hi:[1,0,1]
	v_add_f32_dpp v28, v46, v34 row_half_mirror row_mask:0xf bank_mask:0xf
	v_add_f32_dpp v32, v47, v35 row_half_mirror row_mask:0xf bank_mask:0xf
	v_pk_fma_f32 v[22:23], v[186:187], v[12:13], v[22:23] op_sel_hi:[1,0,1]
	v_add_f32_dpp v28, v28, v28 row_ror:8 row_mask:0xf bank_mask:0xf
	v_add_f32_dpp v32, v32, v32 row_ror:8 row_mask:0xf bank_mask:0xf
	v_pk_fma_f32 v[24:25], v[184:185], v[14:15], v[24:25] op_sel_hi:[1,0,1]
	v_add_f32_dpp v28, v28, v28 quad_perm:[1,0,3,2] row_mask:0xf bank_mask:0xf
	v_add_f32_dpp v32, v32, v32 quad_perm:[1,0,3,2] row_mask:0xf bank_mask:0xf
	v_pk_fma_f32 v[26:27], v[186:187], v[14:15], v[26:27] op_sel_hi:[1,0,1]
	v_add_f32_dpp v28, v28, v28 quad_perm:[2,3,0,1] row_mask:0xf bank_mask:0xf
	v_add_f32_dpp v32, v32, v32 quad_perm:[2,3,0,1] row_mask:0xf bank_mask:0xf
	v_add_f32_e32 v39, v32, v13
	v_mov_b32_dpp v30, v28 row_half_mirror row_mask:0xf bank_mask:0xf
	v_pk_fma_f32 v[20:21], v[92:93], v[28:29], v[20:21] op_sel_hi:[1,0,1] neg_lo:[0,1,0] neg_hi:[0,1,0]
	v_pk_fma_f32 v[22:23], v[94:95], v[28:29], v[22:23] op_sel_hi:[1,0,1] neg_lo:[0,1,0] neg_hi:[0,1,0]
	v_pk_fma_f32 v[24:25], v[92:93], v[30:31], v[24:25] op_sel_hi:[1,0,1] neg_lo:[0,1,0] neg_hi:[0,1,0]
	v_pk_fma_f32 v[26:27], v[94:95], v[30:31], v[26:27] op_sel_hi:[1,0,1] neg_lo:[0,1,0] neg_hi:[0,1,0]
	ds_write_b32 v102, v39 offset:3328
	ds_read_b128 v[148:151], v195 offset:7424
	ds_read_b128 v[160:163], v195 offset:15616
	ds_read_b128 v[184:187], v195 offset:23808
	ds_read_b128 v[92:95], v195 offset:40192
	ds_read_b64 v[12:13], v196 offset:14848
	ds_read_b32 v14, v36 offset:14848
	s_waitcnt lgkmcnt(14)
	v_pk_mul_f32 v[46:47], v[24:25], v[140:141] op_sel_hi:[0,1]
	v_pk_mul_f32 v[34:35], v[20:21], v[140:141] op_sel_hi:[0,1]
	v_pk_fma_f32 v[46:47], v[24:25], v[142:143], v[46:47] op_sel:[1,0,0] op_sel_hi:[1,1,1]
	v_pk_fma_f32 v[34:35], v[20:21], v[142:143], v[34:35] op_sel:[1,0,0] op_sel_hi:[1,1,1]
	v_pk_fma_f32 v[46:47], v[26:27], v[152:153], v[46:47] op_sel_hi:[0,1,1]
	v_pk_fma_f32 v[34:35], v[22:23], v[152:153], v[34:35] op_sel_hi:[0,1,1]
	v_pk_fma_f32 v[46:47], v[26:27], v[154:155], v[46:47] op_sel:[1,0,0] op_sel_hi:[1,1,1]
	v_pk_fma_f32 v[34:35], v[22:23], v[154:155], v[34:35] op_sel:[1,0,0] op_sel_hi:[1,1,1]
	v_pk_mul_f32 v[20:21], v[20:21], v[164:165]
	v_add_f32_dpp v28, v46, v34 row_half_mirror row_mask:0xf bank_mask:0xf
	v_add_f32_dpp v32, v47, v35 row_half_mirror row_mask:0xf bank_mask:0xf
	v_pk_mul_f32 v[22:23], v[22:23], v[166:167]
	v_add_f32_dpp v28, v28, v28 row_ror:8 row_mask:0xf bank_mask:0xf
	v_add_f32_dpp v32, v32, v32 row_ror:8 row_mask:0xf bank_mask:0xf
	v_pk_mul_f32 v[24:25], v[24:25], v[164:165]
	v_add_f32_dpp v28, v28, v28 quad_perm:[1,0,3,2] row_mask:0xf bank_mask:0xf
	v_add_f32_dpp v32, v32, v32 quad_perm:[1,0,3,2] row_mask:0xf bank_mask:0xf
	v_pk_mul_f32 v[26:27], v[26:27], v[166:167]
	v_add_f32_dpp v28, v28, v28 quad_perm:[2,3,0,1] row_mask:0xf bank_mask:0xf
	v_add_f32_dpp v32, v32, v32 quad_perm:[2,3,0,1] row_mask:0xf bank_mask:0xf
	v_pk_fma_f32 v[20:21], v[176:177], v[4:5], v[20:21] op_sel_hi:[1,0,1]
	v_mov_b32_dpp v30, v28 row_half_mirror row_mask:0xf bank_mask:0xf
	v_pk_fma_f32 v[22:23], v[178:179], v[4:5], v[22:23] op_sel_hi:[1,0,1]
	v_pk_fma_f32 v[24:25], v[176:177], v[6:7], v[24:25] op_sel_hi:[1,0,1]
	v_pk_fma_f32 v[26:27], v[178:179], v[6:7], v[26:27] op_sel_hi:[1,0,1]
	v_pk_fma_f32 v[20:21], v[84:85], v[28:29], v[20:21] op_sel_hi:[1,0,1] neg_lo:[0,1,0] neg_hi:[0,1,0]
	v_pk_fma_f32 v[22:23], v[86:87], v[28:29], v[22:23] op_sel_hi:[1,0,1] neg_lo:[0,1,0] neg_hi:[0,1,0]
	v_pk_fma_f32 v[24:25], v[84:85], v[30:31], v[24:25] op_sel_hi:[1,0,1] neg_lo:[0,1,0] neg_hi:[0,1,0]
	v_pk_fma_f32 v[26:27], v[86:87], v[30:31], v[26:27] op_sel_hi:[1,0,1] neg_lo:[0,1,0] neg_hi:[0,1,0]
	v_add_f32_e32 v39, v32, v5
	ds_write_b32 v102, v39 offset:3456
	ds_read_b128 v[140:143], v195 offset:7680
	ds_read_b128 v[152:155], v195 offset:15872
	ds_read_b128 v[176:179], v195 offset:24064
	ds_read_b128 v[84:87], v195 offset:40448
	ds_read_b64 v[4:5], v196 offset:15360
	ds_read_b32 v6, v36 offset:15360
	s_waitcnt lgkmcnt(14)
	v_pk_mul_f32 v[46:47], v[24:25], v[144:145] op_sel_hi:[0,1]
	v_pk_mul_f32 v[34:35], v[20:21], v[144:145] op_sel_hi:[0,1]
	v_pk_fma_f32 v[46:47], v[24:25], v[146:147], v[46:47] op_sel:[1,0,0] op_sel_hi:[1,1,1]
	v_pk_fma_f32 v[34:35], v[20:21], v[146:147], v[34:35] op_sel:[1,0,0] op_sel_hi:[1,1,1]
	v_pk_fma_f32 v[46:47], v[26:27], v[156:157], v[46:47] op_sel_hi:[0,1,1]
	v_pk_fma_f32 v[34:35], v[22:23], v[156:157], v[34:35] op_sel_hi:[0,1,1]
	v_pk_fma_f32 v[46:47], v[26:27], v[158:159], v[46:47] op_sel:[1,0,0] op_sel_hi:[1,1,1]
	v_pk_fma_f32 v[34:35], v[22:23], v[158:159], v[34:35] op_sel:[1,0,0] op_sel_hi:[1,1,1]
	v_pk_fma_f32 v[20:21], v[180:181], v[8:9], v[20:21] op_sel_hi:[1,0,1]
	v_add_f32_dpp v28, v46, v34 row_half_mirror row_mask:0xf bank_mask:0xf
	v_add_f32_dpp v32, v47, v35 row_half_mirror row_mask:0xf bank_mask:0xf
	v_pk_fma_f32 v[22:23], v[182:183], v[8:9], v[22:23] op_sel_hi:[1,0,1]
	v_add_f32_dpp v28, v28, v28 row_ror:8 row_mask:0xf bank_mask:0xf
	v_add_f32_dpp v32, v32, v32 row_ror:8 row_mask:0xf bank_mask:0xf
	v_pk_fma_f32 v[24:25], v[180:181], v[10:11], v[24:25] op_sel_hi:[1,0,1]
	v_add_f32_dpp v28, v28, v28 quad_perm:[1,0,3,2] row_mask:0xf bank_mask:0xf
	v_add_f32_dpp v32, v32, v32 quad_perm:[1,0,3,2] row_mask:0xf bank_mask:0xf
	v_pk_fma_f32 v[26:27], v[182:183], v[10:11], v[26:27] op_sel_hi:[1,0,1]
	v_add_f32_dpp v28, v28, v28 quad_perm:[2,3,0,1] row_mask:0xf bank_mask:0xf
	v_add_f32_dpp v32, v32, v32 quad_perm:[2,3,0,1] row_mask:0xf bank_mask:0xf
	v_add_f32_e32 v39, v32, v9
	v_mov_b32_dpp v30, v28 row_half_mirror row_mask:0xf bank_mask:0xf
	v_pk_fma_f32 v[20:21], v[88:89], v[28:29], v[20:21] op_sel_hi:[1,0,1] neg_lo:[0,1,0] neg_hi:[0,1,0]
	v_pk_fma_f32 v[22:23], v[90:91], v[28:29], v[22:23] op_sel_hi:[1,0,1] neg_lo:[0,1,0] neg_hi:[0,1,0]
	v_pk_fma_f32 v[24:25], v[88:89], v[30:31], v[24:25] op_sel_hi:[1,0,1] neg_lo:[0,1,0] neg_hi:[0,1,0]
	v_pk_fma_f32 v[26:27], v[90:91], v[30:31], v[26:27] op_sel_hi:[1,0,1] neg_lo:[0,1,0] neg_hi:[0,1,0]
	ds_write_b32 v102, v39 offset:3584
	ds_read_b128 v[144:147], v195 offset:7936
	ds_read_b128 v[156:159], v195 offset:16128
	ds_read_b128 v[168:171], v195 offset:32512
	ds_read_b128 v[180:183], v195 offset:24320
	ds_read_b128 v[88:91], v195 offset:40704
	ds_read_b64 v[8:9], v196 offset:15872
	ds_read_b32 v10, v36 offset:15872
	s_waitcnt lgkmcnt(15)
	v_pk_mul_f32 v[46:47], v[24:25], v[148:149] op_sel_hi:[0,1]
	v_pk_mul_f32 v[34:35], v[20:21], v[148:149] op_sel_hi:[0,1]
	v_pk_fma_f32 v[46:47], v[24:25], v[150:151], v[46:47] op_sel:[1,0,0] op_sel_hi:[1,1,1]
	v_pk_fma_f32 v[34:35], v[20:21], v[150:151], v[34:35] op_sel:[1,0,0] op_sel_hi:[1,1,1]
	v_pk_fma_f32 v[46:47], v[26:27], v[160:161], v[46:47] op_sel_hi:[0,1,1]
	v_pk_fma_f32 v[34:35], v[22:23], v[160:161], v[34:35] op_sel_hi:[0,1,1]
	v_pk_fma_f32 v[46:47], v[26:27], v[162:163], v[46:47] op_sel:[1,0,0] op_sel_hi:[1,1,1]
	v_pk_fma_f32 v[34:35], v[22:23], v[162:163], v[34:35] op_sel:[1,0,0] op_sel_hi:[1,1,1]
	v_pk_fma_f32 v[20:21], v[184:185], v[12:13], v[20:21] op_sel_hi:[1,0,1]
	v_add_f32_dpp v28, v46, v34 row_half_mirror row_mask:0xf bank_mask:0xf
	v_add_f32_dpp v32, v47, v35 row_half_mirror row_mask:0xf bank_mask:0xf
	v_pk_fma_f32 v[22:23], v[186:187], v[12:13], v[22:23] op_sel_hi:[1,0,1]
	v_add_f32_dpp v28, v28, v28 row_ror:8 row_mask:0xf bank_mask:0xf
	v_add_f32_dpp v32, v32, v32 row_ror:8 row_mask:0xf bank_mask:0xf
	v_pk_fma_f32 v[24:25], v[184:185], v[14:15], v[24:25] op_sel_hi:[1,0,1]
	v_add_f32_dpp v28, v28, v28 quad_perm:[1,0,3,2] row_mask:0xf bank_mask:0xf
	v_add_f32_dpp v32, v32, v32 quad_perm:[1,0,3,2] row_mask:0xf bank_mask:0xf
	v_pk_fma_f32 v[26:27], v[186:187], v[14:15], v[26:27] op_sel_hi:[1,0,1]
	v_add_f32_dpp v28, v28, v28 quad_perm:[2,3,0,1] row_mask:0xf bank_mask:0xf
	v_add_f32_dpp v32, v32, v32 quad_perm:[2,3,0,1] row_mask:0xf bank_mask:0xf
	v_add_f32_e32 v39, v32, v13
	v_mov_b32_dpp v30, v28 row_half_mirror row_mask:0xf bank_mask:0xf
	v_pk_fma_f32 v[20:21], v[92:93], v[28:29], v[20:21] op_sel_hi:[1,0,1] neg_lo:[0,1,0] neg_hi:[0,1,0]
	v_pk_fma_f32 v[22:23], v[94:95], v[28:29], v[22:23] op_sel_hi:[1,0,1] neg_lo:[0,1,0] neg_hi:[0,1,0]
	v_pk_fma_f32 v[24:25], v[92:93], v[30:31], v[24:25] op_sel_hi:[1,0,1] neg_lo:[0,1,0] neg_hi:[0,1,0]
	v_pk_fma_f32 v[26:27], v[94:95], v[30:31], v[26:27] op_sel_hi:[1,0,1] neg_lo:[0,1,0] neg_hi:[0,1,0]
	ds_write_b32 v102, v39 offset:3712
	s_waitcnt lgkmcnt(9)
	v_pk_mul_f32 v[46:47], v[24:25], v[140:141] op_sel_hi:[0,1]
	v_pk_mul_f32 v[34:35], v[20:21], v[140:141] op_sel_hi:[0,1]
	v_pk_fma_f32 v[46:47], v[24:25], v[142:143], v[46:47] op_sel:[1,0,0] op_sel_hi:[1,1,1]
	v_pk_fma_f32 v[34:35], v[20:21], v[142:143], v[34:35] op_sel:[1,0,0] op_sel_hi:[1,1,1]
	v_pk_fma_f32 v[46:47], v[26:27], v[152:153], v[46:47] op_sel_hi:[0,1,1]
	v_pk_fma_f32 v[34:35], v[22:23], v[152:153], v[34:35] op_sel_hi:[0,1,1]
	v_pk_fma_f32 v[46:47], v[26:27], v[154:155], v[46:47] op_sel:[1,0,0] op_sel_hi:[1,1,1]
	v_pk_fma_f32 v[34:35], v[22:23], v[154:155], v[34:35] op_sel:[1,0,0] op_sel_hi:[1,1,1]
	v_pk_fma_f32 v[20:21], v[176:177], v[4:5], v[20:21] op_sel_hi:[1,0,1]
	v_add_f32_dpp v28, v46, v34 row_half_mirror row_mask:0xf bank_mask:0xf
	v_add_f32_dpp v32, v47, v35 row_half_mirror row_mask:0xf bank_mask:0xf
	v_pk_fma_f32 v[22:23], v[178:179], v[4:5], v[22:23] op_sel_hi:[1,0,1]
	v_add_f32_dpp v28, v28, v28 row_ror:8 row_mask:0xf bank_mask:0xf
	v_add_f32_dpp v32, v32, v32 row_ror:8 row_mask:0xf bank_mask:0xf
	v_pk_fma_f32 v[24:25], v[176:177], v[6:7], v[24:25] op_sel_hi:[1,0,1]
	v_add_f32_dpp v28, v28, v28 quad_perm:[1,0,3,2] row_mask:0xf bank_mask:0xf
	v_add_f32_dpp v32, v32, v32 quad_perm:[1,0,3,2] row_mask:0xf bank_mask:0xf
	v_pk_fma_f32 v[26:27], v[178:179], v[6:7], v[26:27] op_sel_hi:[1,0,1]
	v_add_f32_dpp v28, v28, v28 quad_perm:[2,3,0,1] row_mask:0xf bank_mask:0xf
	v_add_f32_dpp v32, v32, v32 quad_perm:[2,3,0,1] row_mask:0xf bank_mask:0xf
	v_add_f32_e32 v39, v32, v5
	v_mov_b32_dpp v30, v28 row_half_mirror row_mask:0xf bank_mask:0xf
	v_pk_fma_f32 v[20:21], v[84:85], v[28:29], v[20:21] op_sel_hi:[1,0,1] neg_lo:[0,1,0] neg_hi:[0,1,0]
	v_pk_fma_f32 v[22:23], v[86:87], v[28:29], v[22:23] op_sel_hi:[1,0,1] neg_lo:[0,1,0] neg_hi:[0,1,0]
	v_pk_fma_f32 v[24:25], v[84:85], v[30:31], v[24:25] op_sel_hi:[1,0,1] neg_lo:[0,1,0] neg_hi:[0,1,0]
	v_pk_fma_f32 v[26:27], v[86:87], v[30:31], v[26:27] op_sel_hi:[1,0,1] neg_lo:[0,1,0] neg_hi:[0,1,0]
	ds_write_b32 v102, v39 offset:3840
	s_waitcnt lgkmcnt(2)
	v_pk_mul_f32 v[46:47], v[24:25], v[144:145] op_sel_hi:[0,1]
	v_pk_mul_f32 v[34:35], v[20:21], v[144:145] op_sel_hi:[0,1]
	v_pk_fma_f32 v[46:47], v[24:25], v[146:147], v[46:47] op_sel:[1,0,0] op_sel_hi:[1,1,1]
	v_pk_fma_f32 v[34:35], v[20:21], v[146:147], v[34:35] op_sel:[1,0,0] op_sel_hi:[1,1,1]
	v_pk_fma_f32 v[46:47], v[26:27], v[156:157], v[46:47] op_sel_hi:[0,1,1]
	v_pk_fma_f32 v[34:35], v[22:23], v[156:157], v[34:35] op_sel_hi:[0,1,1]
	v_pk_fma_f32 v[46:47], v[26:27], v[158:159], v[46:47] op_sel:[1,0,0] op_sel_hi:[1,1,1]
	v_pk_fma_f32 v[34:35], v[22:23], v[158:159], v[34:35] op_sel:[1,0,0] op_sel_hi:[1,1,1]
	v_pk_mul_f32 v[20:21], v[20:21], v[168:169]
	v_add_f32_dpp v28, v46, v34 row_half_mirror row_mask:0xf bank_mask:0xf
	v_add_f32_dpp v32, v47, v35 row_half_mirror row_mask:0xf bank_mask:0xf
	v_pk_mul_f32 v[22:23], v[22:23], v[170:171]
	v_add_f32_dpp v28, v28, v28 row_ror:8 row_mask:0xf bank_mask:0xf
	v_add_f32_dpp v32, v32, v32 row_ror:8 row_mask:0xf bank_mask:0xf
	v_pk_mul_f32 v[24:25], v[24:25], v[168:169]
	v_add_f32_dpp v28, v28, v28 quad_perm:[1,0,3,2] row_mask:0xf bank_mask:0xf
	v_add_f32_dpp v32, v32, v32 quad_perm:[1,0,3,2] row_mask:0xf bank_mask:0xf
	v_pk_mul_f32 v[26:27], v[26:27], v[170:171]
	v_add_f32_dpp v28, v28, v28 quad_perm:[2,3,0,1] row_mask:0xf bank_mask:0xf
	v_add_f32_dpp v32, v32, v32 quad_perm:[2,3,0,1] row_mask:0xf bank_mask:0xf
	v_pk_fma_f32 v[20:21], v[180:181], v[8:9], v[20:21] op_sel_hi:[1,0,1]
	v_mov_b32_dpp v30, v28 row_half_mirror row_mask:0xf bank_mask:0xf
	v_pk_fma_f32 v[22:23], v[182:183], v[8:9], v[22:23] op_sel_hi:[1,0,1]
	v_pk_fma_f32 v[24:25], v[180:181], v[10:11], v[24:25] op_sel_hi:[1,0,1]
	v_pk_fma_f32 v[26:27], v[182:183], v[10:11], v[26:27] op_sel_hi:[1,0,1]
	v_pk_fma_f32 v[20:21], v[88:89], v[28:29], v[20:21] op_sel_hi:[1,0,1] neg_lo:[0,1,0] neg_hi:[0,1,0]
	v_pk_fma_f32 v[22:23], v[90:91], v[28:29], v[22:23] op_sel_hi:[1,0,1] neg_lo:[0,1,0] neg_hi:[0,1,0]
	v_pk_fma_f32 v[24:25], v[88:89], v[30:31], v[24:25] op_sel_hi:[1,0,1] neg_lo:[0,1,0] neg_hi:[0,1,0]
	v_pk_fma_f32 v[26:27], v[90:91], v[30:31], v[26:27] op_sel_hi:[1,0,1] neg_lo:[0,1,0] neg_hi:[0,1,0]
	v_add_f32_e32 v39, v32, v9
	ds_write_b32 v102, v39 offset:3968
	s_waitcnt lgkmcnt(0)
	s_barrier
	s_add_i32 s8, s8, 1
	s_cmp_eq_u32 s8, 64
	s_cbranch_scc0 .Lrw_scan_loop
	s_setprio 0
	s_branch .LBB0_183
